# placement pin: the 14 GEMM main-loop heads aligned to 64 bytes (.p2align 6), otherwise identical
# speedup vs baseline: 1.0015x; 1.0015x over previous
;     __host__ __device__ bool next(int i, Unit& u) const { const long L = (long)i * G + c; if (L >= (long)nM * nN * nq) return false; const int t = (int)L / nq; u.kq = (int)L % nq; u.pm = t % nM; u.pn = t / nM; return true; }
; template <class Epi, class Sched, bool ALIGN_EPI = false, bool SP2 = false>
; __device__ __forceinline__ void gemm_phase(PG8_LAS unsigned char* lds, const Gemm g, const Sched& S, const Epi& E, int tid_in) {
;     ...
;     for (;;) {
;         const bool has_next = S.next(ui + 1, nxt);
;         const char* nA = has_next ? (const char*)g.A + (size_t)nxt.pm * tsA + (size_t)nxt.kq * g.kqb : cA; const char* nB = has_next ? (const char*)g.Bt + (size_t)nxt.pn * tsB + (size_t)nxt.kq * g.kqb : cB;
;         for (int t = 0; t < nt; t += 2) {
;     ...
; #pragma unroll
;         for (int a = 0; a < 2; ++a)
; #pragma unroll
;             for (int b = 0; b < 2; ++b)
; #pragma unroll
;                 for (int m = 0; m < 4; ++m)
; #pragma unroll
;                     for (int n = 0; n < 2; ++n) acc[a][b][m][n] = (f32x4){0.f, 0.f, 0.f, 0.f};
;         cur = nxt; cA = nA; cB = nB; ++ui;
.LBB0_242:
	v_mov_b32_e32 v127, 0
	s_andn2_b64 vcc, exec, s[16:17]
	v_mov_b32_e32 v126, v127
	v_mov_b32_e32 v125, v127
	v_mov_b32_e32 v124, v127
	v_mov_b32_e32 v123, v127
	v_mov_b32_e32 v122, v127
	v_mov_b32_e32 v121, v127
	v_mov_b32_e32 v120, v127
	v_mov_b32_e32 v115, v127
	v_mov_b32_e32 v114, v127
	v_mov_b32_e32 v113, v127
	v_mov_b32_e32 v112, v127
	v_mov_b32_e32 v107, v127
	v_mov_b32_e32 v106, v127
	v_mov_b32_e32 v105, v127
	v_mov_b32_e32 v104, v127
	v_mov_b32_e32 v99, v127
	v_mov_b32_e32 v98, v127
	v_mov_b32_e32 v97, v127
	v_mov_b32_e32 v96, v127
	v_mov_b32_e32 v91, v127
	v_mov_b32_e32 v90, v127
	v_mov_b32_e32 v89, v127
	v_mov_b32_e32 v88, v127
	v_mov_b32_e32 v83, v127
	v_mov_b32_e32 v82, v127
	v_mov_b32_e32 v81, v127
	v_mov_b32_e32 v80, v127
	v_mov_b32_e32 v75, v127
	v_mov_b32_e32 v74, v127
	v_mov_b32_e32 v73, v127
	v_mov_b32_e32 v72, v127
	v_mov_b32_e32 v131, v127
	v_mov_b32_e32 v130, v127
	v_mov_b32_e32 v129, v127
	v_mov_b32_e32 v128, v127
	v_mov_b32_e32 v119, v127
	v_mov_b32_e32 v118, v127
	v_mov_b32_e32 v117, v127
	v_mov_b32_e32 v116, v127
	v_mov_b32_e32 v111, v127
	v_mov_b32_e32 v110, v127
	v_mov_b32_e32 v109, v127
	v_mov_b32_e32 v108, v127
	v_mov_b32_e32 v103, v127
	v_mov_b32_e32 v102, v127
	v_mov_b32_e32 v101, v127
	v_mov_b32_e32 v100, v127
	v_mov_b32_e32 v95, v127
	v_mov_b32_e32 v94, v127
	v_mov_b32_e32 v93, v127
	v_mov_b32_e32 v92, v127
	v_mov_b32_e32 v87, v127
	v_mov_b32_e32 v86, v127
	v_mov_b32_e32 v85, v127
	v_mov_b32_e32 v84, v127
	v_mov_b32_e32 v79, v127
	v_mov_b32_e32 v78, v127
	v_mov_b32_e32 v77, v127
	v_mov_b32_e32 v76, v127
	v_mov_b32_e32 v71, v127
	v_mov_b32_e32 v70, v127
	v_mov_b32_e32 v69, v127
	v_mov_b32_e32 v68, v127
	v_mov_b32_e32 v67, v127
	v_mov_b32_e32 v66, v127
	v_mov_b32_e32 v65, v127
	v_mov_b32_e32 v64, v127
	v_mov_b32_e32 v59, v127
	v_mov_b32_e32 v58, v127
	v_mov_b32_e32 v57, v127
	v_mov_b32_e32 v56, v127
	v_mov_b32_e32 v51, v127
	v_mov_b32_e32 v50, v127
	v_mov_b32_e32 v49, v127
	v_mov_b32_e32 v48, v127
	v_mov_b32_e32 v43, v127
	v_mov_b32_e32 v42, v127
	v_mov_b32_e32 v41, v127
	v_mov_b32_e32 v40, v127
	v_mov_b32_e32 v35, v127
	v_mov_b32_e32 v34, v127
	v_mov_b32_e32 v33, v127
	v_mov_b32_e32 v32, v127
	v_mov_b32_e32 v27, v127
	v_mov_b32_e32 v26, v127
	v_mov_b32_e32 v25, v127
	v_mov_b32_e32 v24, v127
	v_mov_b32_e32 v19, v127
	v_mov_b32_e32 v18, v127
	v_mov_b32_e32 v17, v127
	v_mov_b32_e32 v16, v127
	v_mov_b32_e32 v11, v127
	v_mov_b32_e32 v10, v127
	v_mov_b32_e32 v9, v127
	v_mov_b32_e32 v8, v127
	v_mov_b32_e32 v63, v127
	v_mov_b32_e32 v62, v127
	v_mov_b32_e32 v61, v127
	v_mov_b32_e32 v60, v127
	v_mov_b32_e32 v55, v127
	v_mov_b32_e32 v54, v127
	v_mov_b32_e32 v53, v127
	v_mov_b32_e32 v52, v127
	v_mov_b32_e32 v47, v127
	v_mov_b32_e32 v46, v127
	v_mov_b32_e32 v45, v127
	v_mov_b32_e32 v44, v127
	v_mov_b32_e32 v39, v127
	v_mov_b32_e32 v38, v127
	v_mov_b32_e32 v37, v127
	v_mov_b32_e32 v36, v127
	v_mov_b32_e32 v31, v127
	v_mov_b32_e32 v30, v127
	v_mov_b32_e32 v29, v127
	v_mov_b32_e32 v28, v127
	v_mov_b32_e32 v23, v127
	v_mov_b32_e32 v22, v127
	v_mov_b32_e32 v21, v127
	v_mov_b32_e32 v20, v127
	v_mov_b32_e32 v15, v127
	v_mov_b32_e32 v14, v127
	v_mov_b32_e32 v13, v127
	v_mov_b32_e32 v12, v127
	v_mov_b32_e32 v7, v127
	v_mov_b32_e32 v6, v127
	v_mov_b32_e32 v5, v127
	v_mov_b32_e32 v4, v127
	s_cbranch_vccnz .LBB0_245
	s_add_u32 s51, s22, 0x100
	s_addc_u32 s52, s23, 0
	s_add_u32 s22, s24, 0x80
	v_mov_b32_e32 v4, 0
	s_addc_u32 s23, s25, 0
	s_mov_b32 s53, 2
	v_mov_b32_e32 v5, v4
	v_mov_b32_e32 v6, v4
	v_mov_b32_e32 v7, v4
	v_mov_b32_e32 v12, v4
	v_mov_b32_e32 v13, v4
	v_mov_b32_e32 v14, v4
	v_mov_b32_e32 v15, v4
	v_mov_b32_e32 v20, v4
	v_mov_b32_e32 v21, v4
	v_mov_b32_e32 v22, v4
	v_mov_b32_e32 v23, v4
	v_mov_b32_e32 v28, v4
	v_mov_b32_e32 v29, v4
	v_mov_b32_e32 v30, v4
	v_mov_b32_e32 v31, v4
	v_mov_b32_e32 v36, v4
	v_mov_b32_e32 v37, v4
	v_mov_b32_e32 v38, v4
	v_mov_b32_e32 v39, v4
	v_mov_b32_e32 v44, v4
	v_mov_b32_e32 v45, v4
	v_mov_b32_e32 v46, v4
	v_mov_b32_e32 v47, v4
	v_mov_b32_e32 v52, v4
	v_mov_b32_e32 v53, v4
	v_mov_b32_e32 v54, v4
	v_mov_b32_e32 v55, v4
	v_mov_b32_e32 v60, v4
	v_mov_b32_e32 v61, v4
	v_mov_b32_e32 v62, v4
	v_mov_b32_e32 v63, v4
	v_mov_b32_e32 v8, v4
	v_mov_b32_e32 v9, v4
	v_mov_b32_e32 v10, v4
	v_mov_b32_e32 v11, v4
	v_mov_b32_e32 v16, v4
	v_mov_b32_e32 v17, v4
	v_mov_b32_e32 v18, v4
	v_mov_b32_e32 v19, v4
	v_mov_b32_e32 v24, v4
	v_mov_b32_e32 v25, v4
	v_mov_b32_e32 v26, v4
	v_mov_b32_e32 v27, v4
	v_mov_b32_e32 v32, v4
	v_mov_b32_e32 v33, v4
	v_mov_b32_e32 v34, v4
	v_mov_b32_e32 v35, v4
	v_mov_b32_e32 v40, v4
	v_mov_b32_e32 v41, v4
	v_mov_b32_e32 v42, v4
	v_mov_b32_e32 v43, v4
	v_mov_b32_e32 v48, v4
	v_mov_b32_e32 v49, v4
	v_mov_b32_e32 v50, v4
	v_mov_b32_e32 v51, v4
	v_mov_b32_e32 v56, v4
	v_mov_b32_e32 v57, v4
	v_mov_b32_e32 v58, v4
	v_mov_b32_e32 v59, v4
	v_mov_b32_e32 v64, v4
	v_mov_b32_e32 v65, v4
	v_mov_b32_e32 v66, v4
	v_mov_b32_e32 v67, v4
	v_mov_b32_e32 v68, v4
	v_mov_b32_e32 v69, v4
	v_mov_b32_e32 v70, v4
	v_mov_b32_e32 v71, v4
	v_mov_b32_e32 v76, v4
	v_mov_b32_e32 v77, v4
	v_mov_b32_e32 v78, v4
	v_mov_b32_e32 v79, v4
	v_mov_b32_e32 v84, v4
	v_mov_b32_e32 v85, v4
	v_mov_b32_e32 v86, v4
	v_mov_b32_e32 v87, v4
	v_mov_b32_e32 v92, v4
	v_mov_b32_e32 v93, v4
	v_mov_b32_e32 v94, v4
	v_mov_b32_e32 v95, v4
	v_mov_b32_e32 v100, v4
	v_mov_b32_e32 v101, v4
	v_mov_b32_e32 v102, v4
	v_mov_b32_e32 v103, v4
	v_mov_b32_e32 v108, v4
	v_mov_b32_e32 v109, v4
	v_mov_b32_e32 v110, v4
	v_mov_b32_e32 v111, v4
	v_mov_b32_e32 v116, v4
	v_mov_b32_e32 v117, v4
	v_mov_b32_e32 v118, v4
	v_mov_b32_e32 v119, v4
	v_mov_b32_e32 v128, v4
	v_mov_b32_e32 v129, v4
	v_mov_b32_e32 v130, v4
	v_mov_b32_e32 v131, v4
	v_mov_b32_e32 v72, v4
	v_mov_b32_e32 v73, v4
	v_mov_b32_e32 v74, v4
	v_mov_b32_e32 v75, v4
	v_mov_b32_e32 v80, v4
	v_mov_b32_e32 v81, v4
	v_mov_b32_e32 v82, v4
	v_mov_b32_e32 v83, v4
	v_mov_b32_e32 v88, v4
	v_mov_b32_e32 v89, v4
	v_mov_b32_e32 v90, v4
	v_mov_b32_e32 v91, v4
	v_mov_b32_e32 v96, v4
	v_mov_b32_e32 v97, v4
	v_mov_b32_e32 v98, v4
	v_mov_b32_e32 v99, v4
	v_mov_b32_e32 v104, v4
	v_mov_b32_e32 v105, v4
	v_mov_b32_e32 v106, v4
	v_mov_b32_e32 v107, v4
	v_mov_b32_e32 v112, v4
	v_mov_b32_e32 v113, v4
	v_mov_b32_e32 v114, v4
	v_mov_b32_e32 v115, v4
	v_mov_b32_e32 v120, v4
	v_mov_b32_e32 v121, v4
	v_mov_b32_e32 v122, v4
	v_mov_b32_e32 v123, v4
	v_mov_b32_e32 v124, v4
	v_mov_b32_e32 v125, v4
	v_mov_b32_e32 v126, v4
	v_mov_b32_e32 v127, v4
	.p2align	6

;     __host__ __device__ bool next(int i, Unit& u) const { const long L = (long)i * G + c; if (L >= (long)nM * nN * nq) return false; const int t = (int)L / nq; u.kq = (int)L % nq; u.pm = t % nM; u.pn = t / nM; return true; }
; template <class Epi, class Sched, bool ALIGN_EPI = false, bool SP2 = false>
; __device__ __forceinline__ void gemm_phase(PG8_LAS unsigned char* lds, const Gemm g, const Sched& S, const Epi& E, int tid_in) {
;     ...
;     for (;;) {
;         const bool has_next = S.next(ui + 1, nxt);
;         const char* nA = has_next ? (const char*)g.A + (size_t)nxt.pm * tsA + (size_t)nxt.kq * g.kqb : cA; const char* nB = has_next ? (const char*)g.Bt + (size_t)nxt.pn * tsB + (size_t)nxt.kq * g.kqb : cB;
;         for (int t = 0; t < nt; t += 2) {
;     ...
; #pragma unroll
;         for (int a = 0; a < 2; ++a)
; #pragma unroll
;             for (int b = 0; b < 2; ++b)
; #pragma unroll
;                 for (int m = 0; m < 4; ++m)
; #pragma unroll
;                     for (int n = 0; n < 2; ++n) acc[a][b][m][n] = (f32x4){0.f, 0.f, 0.f, 0.f};
;         cur = nxt; cA = nA; cB = nB; ++ui;
.LBB0_319:
	v_mov_b32_e32 v131, 0
	s_andn2_b64 vcc, exec, s[24:25]
	v_mov_b32_e32 v130, v131
	v_mov_b32_e32 v129, v131
	v_mov_b32_e32 v128, v131
	v_mov_b32_e32 v127, v131
	v_mov_b32_e32 v126, v131
	v_mov_b32_e32 v125, v131
	v_mov_b32_e32 v124, v131
	v_mov_b32_e32 v123, v131
	v_mov_b32_e32 v122, v131
	v_mov_b32_e32 v121, v131
	v_mov_b32_e32 v120, v131
	v_mov_b32_e32 v119, v131
	v_mov_b32_e32 v118, v131
	v_mov_b32_e32 v117, v131
	v_mov_b32_e32 v116, v131
	v_mov_b32_e32 v115, v131
	v_mov_b32_e32 v114, v131
	v_mov_b32_e32 v113, v131
	v_mov_b32_e32 v112, v131
	v_mov_b32_e32 v111, v131
	v_mov_b32_e32 v110, v131
	v_mov_b32_e32 v109, v131
	v_mov_b32_e32 v108, v131
	v_mov_b32_e32 v107, v131
	v_mov_b32_e32 v106, v131
	v_mov_b32_e32 v105, v131
	v_mov_b32_e32 v104, v131
	v_mov_b32_e32 v103, v131
	v_mov_b32_e32 v102, v131
	v_mov_b32_e32 v101, v131
	v_mov_b32_e32 v100, v131
	v_mov_b32_e32 v67, v131
	v_mov_b32_e32 v66, v131
	v_mov_b32_e32 v65, v131
	v_mov_b32_e32 v64, v131
	v_mov_b32_e32 v59, v131
	v_mov_b32_e32 v58, v131
	v_mov_b32_e32 v57, v131
	v_mov_b32_e32 v56, v131
	v_mov_b32_e32 v63, v131
	v_mov_b32_e32 v62, v131
	v_mov_b32_e32 v61, v131
	v_mov_b32_e32 v60, v131
	v_mov_b32_e32 v55, v131
	v_mov_b32_e32 v54, v131
	v_mov_b32_e32 v53, v131
	v_mov_b32_e32 v52, v131
	v_mov_b32_e32 v51, v131
	v_mov_b32_e32 v50, v131
	v_mov_b32_e32 v49, v131
	v_mov_b32_e32 v48, v131
	v_mov_b32_e32 v43, v131
	v_mov_b32_e32 v42, v131
	v_mov_b32_e32 v41, v131
	v_mov_b32_e32 v40, v131
	v_mov_b32_e32 v47, v131
	v_mov_b32_e32 v46, v131
	v_mov_b32_e32 v45, v131
	v_mov_b32_e32 v44, v131
	v_mov_b32_e32 v39, v131
	v_mov_b32_e32 v38, v131
	v_mov_b32_e32 v37, v131
	v_mov_b32_e32 v36, v131
	v_mov_b32_e32 v99, v131
	v_mov_b32_e32 v98, v131
	v_mov_b32_e32 v97, v131
	v_mov_b32_e32 v96, v131
	v_mov_b32_e32 v95, v131
	v_mov_b32_e32 v94, v131
	v_mov_b32_e32 v93, v131
	v_mov_b32_e32 v92, v131
	v_mov_b32_e32 v91, v131
	v_mov_b32_e32 v90, v131
	v_mov_b32_e32 v89, v131
	v_mov_b32_e32 v88, v131
	v_mov_b32_e32 v87, v131
	v_mov_b32_e32 v86, v131
	v_mov_b32_e32 v85, v131
	v_mov_b32_e32 v84, v131
	v_mov_b32_e32 v83, v131
	v_mov_b32_e32 v82, v131
	v_mov_b32_e32 v81, v131
	v_mov_b32_e32 v80, v131
	v_mov_b32_e32 v79, v131
	v_mov_b32_e32 v78, v131
	v_mov_b32_e32 v77, v131
	v_mov_b32_e32 v76, v131
	v_mov_b32_e32 v75, v131
	v_mov_b32_e32 v74, v131
	v_mov_b32_e32 v73, v131
	v_mov_b32_e32 v72, v131
	v_mov_b32_e32 v71, v131
	v_mov_b32_e32 v70, v131
	v_mov_b32_e32 v69, v131
	v_mov_b32_e32 v68, v131
	v_mov_b32_e32 v35, v131
	v_mov_b32_e32 v34, v131
	v_mov_b32_e32 v33, v131
	v_mov_b32_e32 v32, v131
	v_mov_b32_e32 v31, v131
	v_mov_b32_e32 v30, v131
	v_mov_b32_e32 v29, v131
	v_mov_b32_e32 v28, v131
	v_mov_b32_e32 v27, v131
	v_mov_b32_e32 v26, v131
	v_mov_b32_e32 v25, v131
	v_mov_b32_e32 v24, v131
	v_mov_b32_e32 v15, v131
	v_mov_b32_e32 v14, v131
	v_mov_b32_e32 v13, v131
	v_mov_b32_e32 v12, v131
	v_mov_b32_e32 v23, v131
	v_mov_b32_e32 v22, v131
	v_mov_b32_e32 v21, v131
	v_mov_b32_e32 v20, v131
	v_mov_b32_e32 v11, v131
	v_mov_b32_e32 v10, v131
	v_mov_b32_e32 v9, v131
	v_mov_b32_e32 v8, v131
	v_mov_b32_e32 v19, v131
	v_mov_b32_e32 v18, v131
	v_mov_b32_e32 v17, v131
	v_mov_b32_e32 v16, v131
	v_mov_b32_e32 v7, v131
	v_mov_b32_e32 v6, v131
	v_mov_b32_e32 v5, v131
	v_mov_b32_e32 v4, v131
	s_cbranch_vccnz .LBB0_323
	s_add_u32 s76, s40, 0x100
	s_addc_u32 s77, s41, 0
	s_add_u32 s4, s42, 0x80
	v_mov_b32_e32 v4, 0
	s_addc_u32 s5, s43, 0
	s_mov_b32 s42, 2
	v_mov_b32_e32 v5, v4
	v_mov_b32_e32 v6, v4
	v_mov_b32_e32 v7, v4
	v_mov_b32_e32 v16, v4
	v_mov_b32_e32 v17, v4
	v_mov_b32_e32 v18, v4
	v_mov_b32_e32 v19, v4
	v_mov_b32_e32 v8, v4
	v_mov_b32_e32 v9, v4
	v_mov_b32_e32 v10, v4
	v_mov_b32_e32 v11, v4
	v_mov_b32_e32 v20, v4
	v_mov_b32_e32 v21, v4
	v_mov_b32_e32 v22, v4
	v_mov_b32_e32 v23, v4
	v_mov_b32_e32 v12, v4
	v_mov_b32_e32 v13, v4
	v_mov_b32_e32 v14, v4
	v_mov_b32_e32 v15, v4
	v_mov_b32_e32 v24, v4
	v_mov_b32_e32 v25, v4
	v_mov_b32_e32 v26, v4
	v_mov_b32_e32 v27, v4
	v_mov_b32_e32 v28, v4
	v_mov_b32_e32 v29, v4
	v_mov_b32_e32 v30, v4
	v_mov_b32_e32 v31, v4
	v_mov_b32_e32 v32, v4
	v_mov_b32_e32 v33, v4
	v_mov_b32_e32 v34, v4
	v_mov_b32_e32 v35, v4
	v_mov_b32_e32 v68, v4
	v_mov_b32_e32 v69, v4
	v_mov_b32_e32 v70, v4
	v_mov_b32_e32 v71, v4
	v_mov_b32_e32 v72, v4
	v_mov_b32_e32 v73, v4
	v_mov_b32_e32 v74, v4
	v_mov_b32_e32 v75, v4
	v_mov_b32_e32 v76, v4
	v_mov_b32_e32 v77, v4
	v_mov_b32_e32 v78, v4
	v_mov_b32_e32 v79, v4
	v_mov_b32_e32 v80, v4
	v_mov_b32_e32 v81, v4
	v_mov_b32_e32 v82, v4
	v_mov_b32_e32 v83, v4
	v_mov_b32_e32 v84, v4
	v_mov_b32_e32 v85, v4
	v_mov_b32_e32 v86, v4
	v_mov_b32_e32 v87, v4
	v_mov_b32_e32 v88, v4
	v_mov_b32_e32 v89, v4
	v_mov_b32_e32 v90, v4
	v_mov_b32_e32 v91, v4
	v_mov_b32_e32 v92, v4
	v_mov_b32_e32 v93, v4
	v_mov_b32_e32 v94, v4
	v_mov_b32_e32 v95, v4
	v_mov_b32_e32 v96, v4
	v_mov_b32_e32 v97, v4
	v_mov_b32_e32 v98, v4
	v_mov_b32_e32 v99, v4
	v_mov_b32_e32 v36, v4
	v_mov_b32_e32 v37, v4
	v_mov_b32_e32 v38, v4
	v_mov_b32_e32 v39, v4
	v_mov_b32_e32 v44, v4
	v_mov_b32_e32 v45, v4
	v_mov_b32_e32 v46, v4
	v_mov_b32_e32 v47, v4
	v_mov_b32_e32 v40, v4
	v_mov_b32_e32 v41, v4
	v_mov_b32_e32 v42, v4
	v_mov_b32_e32 v43, v4
	v_mov_b32_e32 v48, v4
	v_mov_b32_e32 v49, v4
	v_mov_b32_e32 v50, v4
	v_mov_b32_e32 v51, v4
	v_mov_b32_e32 v52, v4
	v_mov_b32_e32 v53, v4
	v_mov_b32_e32 v54, v4
	v_mov_b32_e32 v55, v4
	v_mov_b32_e32 v60, v4
	v_mov_b32_e32 v61, v4
	v_mov_b32_e32 v62, v4
	v_mov_b32_e32 v63, v4
	v_mov_b32_e32 v56, v4
	v_mov_b32_e32 v57, v4
	v_mov_b32_e32 v58, v4
	v_mov_b32_e32 v59, v4
	v_mov_b32_e32 v64, v4
	v_mov_b32_e32 v65, v4
	v_mov_b32_e32 v66, v4
	v_mov_b32_e32 v67, v4
	v_mov_b32_e32 v100, v4
	v_mov_b32_e32 v101, v4
	v_mov_b32_e32 v102, v4
	v_mov_b32_e32 v103, v4
	v_mov_b32_e32 v104, v4
	v_mov_b32_e32 v105, v4
	v_mov_b32_e32 v106, v4
	v_mov_b32_e32 v107, v4
	v_mov_b32_e32 v108, v4
	v_mov_b32_e32 v109, v4
	v_mov_b32_e32 v110, v4
	v_mov_b32_e32 v111, v4
	v_mov_b32_e32 v112, v4
	v_mov_b32_e32 v113, v4
	v_mov_b32_e32 v114, v4
	v_mov_b32_e32 v115, v4
	v_mov_b32_e32 v116, v4
	v_mov_b32_e32 v117, v4
	v_mov_b32_e32 v118, v4
	v_mov_b32_e32 v119, v4
	v_mov_b32_e32 v120, v4
	v_mov_b32_e32 v121, v4
	v_mov_b32_e32 v122, v4
	v_mov_b32_e32 v123, v4
	v_mov_b32_e32 v124, v4
	v_mov_b32_e32 v125, v4
	v_mov_b32_e32 v126, v4
	v_mov_b32_e32 v127, v4
	v_mov_b32_e32 v128, v4
	v_mov_b32_e32 v129, v4
	v_mov_b32_e32 v130, v4
	v_mov_b32_e32 v131, v4
	.p2align	6

;     __host__ __device__ bool next(int i, Unit& u) const { const long L = (long)i * G + c; if (L >= (long)nM * nN * nq) return false; const int t = (int)L / nq; u.kq = (int)L % nq; u.pm = t % nM; u.pn = t / nM; return true; }
; template <class Epi, class Sched, bool ALIGN_EPI = false, bool SP2 = false>
; __device__ __forceinline__ void gemm_phase(PG8_LAS unsigned char* lds, const Gemm g, const Sched& S, const Epi& E, int tid_in) {
;     ...
;     for (;;) {
;         const bool has_next = S.next(ui + 1, nxt);
;         const char* nA = has_next ? (const char*)g.A + (size_t)nxt.pm * tsA + (size_t)nxt.kq * g.kqb : cA; const char* nB = has_next ? (const char*)g.Bt + (size_t)nxt.pn * tsB + (size_t)nxt.kq * g.kqb : cB;
;         for (int t = 0; t < nt; t += 2) {
;     ...
; #pragma unroll
;         for (int a = 0; a < 2; ++a)
; #pragma unroll
;             for (int b = 0; b < 2; ++b)
; #pragma unroll
;                 for (int m = 0; m < 4; ++m)
; #pragma unroll
;                     for (int n = 0; n < 2; ++n) acc[a][b][m][n] = (f32x4){0.f, 0.f, 0.f, 0.f};
;         cur = nxt; cA = nA; cB = nB; ++ui;
.LBB0_350:
	v_mov_b32_e32 v127, 0
	s_andn2_b64 vcc, exec, s[0:1]
	v_mov_b32_e32 v126, v127
	v_mov_b32_e32 v125, v127
	v_mov_b32_e32 v124, v127
	v_mov_b32_e32 v131, v127
	v_mov_b32_e32 v130, v127
	v_mov_b32_e32 v129, v127
	v_mov_b32_e32 v128, v127
	v_mov_b32_e32 v115, v127
	v_mov_b32_e32 v114, v127
	v_mov_b32_e32 v113, v127
	v_mov_b32_e32 v112, v127
	v_mov_b32_e32 v111, v127
	v_mov_b32_e32 v110, v127
	v_mov_b32_e32 v109, v127
	v_mov_b32_e32 v108, v127
	v_mov_b32_e32 v99, v127
	v_mov_b32_e32 v98, v127
	v_mov_b32_e32 v97, v127
	v_mov_b32_e32 v96, v127
	v_mov_b32_e32 v95, v127
	v_mov_b32_e32 v94, v127
	v_mov_b32_e32 v93, v127
	v_mov_b32_e32 v92, v127
	v_mov_b32_e32 v83, v127
	v_mov_b32_e32 v82, v127
	v_mov_b32_e32 v81, v127
	v_mov_b32_e32 v80, v127
	v_mov_b32_e32 v79, v127
	v_mov_b32_e32 v78, v127
	v_mov_b32_e32 v77, v127
	v_mov_b32_e32 v76, v127
	v_mov_b32_e32 v123, v127
	v_mov_b32_e32 v122, v127
	v_mov_b32_e32 v121, v127
	v_mov_b32_e32 v120, v127
	v_mov_b32_e32 v119, v127
	v_mov_b32_e32 v118, v127
	v_mov_b32_e32 v117, v127
	v_mov_b32_e32 v116, v127
	v_mov_b32_e32 v107, v127
	v_mov_b32_e32 v106, v127
	v_mov_b32_e32 v105, v127
	v_mov_b32_e32 v104, v127
	v_mov_b32_e32 v103, v127
	v_mov_b32_e32 v102, v127
	v_mov_b32_e32 v101, v127
	v_mov_b32_e32 v100, v127
	v_mov_b32_e32 v91, v127
	v_mov_b32_e32 v90, v127
	v_mov_b32_e32 v89, v127
	v_mov_b32_e32 v88, v127
	v_mov_b32_e32 v87, v127
	v_mov_b32_e32 v86, v127
	v_mov_b32_e32 v85, v127
	v_mov_b32_e32 v84, v127
	v_mov_b32_e32 v75, v127
	v_mov_b32_e32 v74, v127
	v_mov_b32_e32 v73, v127
	v_mov_b32_e32 v72, v127
	v_mov_b32_e32 v71, v127
	v_mov_b32_e32 v70, v127
	v_mov_b32_e32 v69, v127
	v_mov_b32_e32 v68, v127
	v_mov_b32_e32 v67, v127
	v_mov_b32_e32 v66, v127
	v_mov_b32_e32 v65, v127
	v_mov_b32_e32 v64, v127
	v_mov_b32_e32 v63, v127
	v_mov_b32_e32 v62, v127
	v_mov_b32_e32 v61, v127
	v_mov_b32_e32 v60, v127
	v_mov_b32_e32 v51, v127
	v_mov_b32_e32 v50, v127
	v_mov_b32_e32 v49, v127
	v_mov_b32_e32 v48, v127
	v_mov_b32_e32 v47, v127
	v_mov_b32_e32 v46, v127
	v_mov_b32_e32 v45, v127
	v_mov_b32_e32 v44, v127
	v_mov_b32_e32 v35, v127
	v_mov_b32_e32 v34, v127
	v_mov_b32_e32 v33, v127
	v_mov_b32_e32 v32, v127
	v_mov_b32_e32 v31, v127
	v_mov_b32_e32 v30, v127
	v_mov_b32_e32 v29, v127
	v_mov_b32_e32 v28, v127
	v_mov_b32_e32 v19, v127
	v_mov_b32_e32 v18, v127
	v_mov_b32_e32 v17, v127
	v_mov_b32_e32 v16, v127
	v_mov_b32_e32 v15, v127
	v_mov_b32_e32 v14, v127
	v_mov_b32_e32 v13, v127
	v_mov_b32_e32 v12, v127
	v_mov_b32_e32 v59, v127
	v_mov_b32_e32 v58, v127
	v_mov_b32_e32 v57, v127
	v_mov_b32_e32 v56, v127
	v_mov_b32_e32 v55, v127
	v_mov_b32_e32 v54, v127
	v_mov_b32_e32 v53, v127
	v_mov_b32_e32 v52, v127
	v_mov_b32_e32 v43, v127
	v_mov_b32_e32 v42, v127
	v_mov_b32_e32 v41, v127
	v_mov_b32_e32 v40, v127
	v_mov_b32_e32 v39, v127
	v_mov_b32_e32 v38, v127
	v_mov_b32_e32 v37, v127
	v_mov_b32_e32 v36, v127
	v_mov_b32_e32 v27, v127
	v_mov_b32_e32 v26, v127
	v_mov_b32_e32 v25, v127
	v_mov_b32_e32 v24, v127
	v_mov_b32_e32 v23, v127
	v_mov_b32_e32 v22, v127
	v_mov_b32_e32 v21, v127
	v_mov_b32_e32 v20, v127
	v_mov_b32_e32 v11, v127
	v_mov_b32_e32 v10, v127
	v_mov_b32_e32 v9, v127
	v_mov_b32_e32 v8, v127
	v_mov_b32_e32 v7, v127
	v_mov_b32_e32 v6, v127
	v_mov_b32_e32 v5, v127
	v_mov_b32_e32 v4, v127
	s_cbranch_vccnz .LBB0_353
	s_add_u32 s53, s22, 0x100
	s_addc_u32 s54, s23, 0
	s_add_u32 s22, s24, 0x80
	v_mov_b32_e32 v4, 0
	s_addc_u32 s23, s25, 0
	s_mov_b32 s55, 2
	v_mov_b32_e32 v5, v4
	v_mov_b32_e32 v6, v4
	v_mov_b32_e32 v7, v4
	v_mov_b32_e32 v8, v4
	v_mov_b32_e32 v9, v4
	v_mov_b32_e32 v10, v4
	v_mov_b32_e32 v11, v4
	v_mov_b32_e32 v20, v4
	v_mov_b32_e32 v21, v4
	v_mov_b32_e32 v22, v4
	v_mov_b32_e32 v23, v4
	v_mov_b32_e32 v24, v4
	v_mov_b32_e32 v25, v4
	v_mov_b32_e32 v26, v4
	v_mov_b32_e32 v27, v4
	v_mov_b32_e32 v36, v4
	v_mov_b32_e32 v37, v4
	v_mov_b32_e32 v38, v4
	v_mov_b32_e32 v39, v4
	v_mov_b32_e32 v40, v4
	v_mov_b32_e32 v41, v4
	v_mov_b32_e32 v42, v4
	v_mov_b32_e32 v43, v4
	v_mov_b32_e32 v52, v4
	v_mov_b32_e32 v53, v4
	v_mov_b32_e32 v54, v4
	v_mov_b32_e32 v55, v4
	v_mov_b32_e32 v56, v4
	v_mov_b32_e32 v57, v4
	v_mov_b32_e32 v58, v4
	v_mov_b32_e32 v59, v4
	v_mov_b32_e32 v12, v4
	v_mov_b32_e32 v13, v4
	v_mov_b32_e32 v14, v4
	v_mov_b32_e32 v15, v4
	v_mov_b32_e32 v16, v4
	v_mov_b32_e32 v17, v4
	v_mov_b32_e32 v18, v4
	v_mov_b32_e32 v19, v4
	v_mov_b32_e32 v28, v4
	v_mov_b32_e32 v29, v4
	v_mov_b32_e32 v30, v4
	v_mov_b32_e32 v31, v4
	v_mov_b32_e32 v32, v4
	v_mov_b32_e32 v33, v4
	v_mov_b32_e32 v34, v4
	v_mov_b32_e32 v35, v4
	v_mov_b32_e32 v44, v4
	v_mov_b32_e32 v45, v4
	v_mov_b32_e32 v46, v4
	v_mov_b32_e32 v47, v4
	v_mov_b32_e32 v48, v4
	v_mov_b32_e32 v49, v4
	v_mov_b32_e32 v50, v4
	v_mov_b32_e32 v51, v4
	v_mov_b32_e32 v60, v4
	v_mov_b32_e32 v61, v4
	v_mov_b32_e32 v62, v4
	v_mov_b32_e32 v63, v4
	v_mov_b32_e32 v64, v4
	v_mov_b32_e32 v65, v4
	v_mov_b32_e32 v66, v4
	v_mov_b32_e32 v67, v4
	v_mov_b32_e32 v68, v4
	v_mov_b32_e32 v69, v4
	v_mov_b32_e32 v70, v4
	v_mov_b32_e32 v71, v4
	v_mov_b32_e32 v72, v4
	v_mov_b32_e32 v73, v4
	v_mov_b32_e32 v74, v4
	v_mov_b32_e32 v75, v4
	v_mov_b32_e32 v84, v4
	v_mov_b32_e32 v85, v4
	v_mov_b32_e32 v86, v4
	v_mov_b32_e32 v87, v4
	v_mov_b32_e32 v88, v4
	v_mov_b32_e32 v89, v4
	v_mov_b32_e32 v90, v4
	v_mov_b32_e32 v91, v4
	v_mov_b32_e32 v100, v4
	v_mov_b32_e32 v101, v4
	v_mov_b32_e32 v102, v4
	v_mov_b32_e32 v103, v4
	v_mov_b32_e32 v104, v4
	v_mov_b32_e32 v105, v4
	v_mov_b32_e32 v106, v4
	v_mov_b32_e32 v107, v4
	v_mov_b32_e32 v116, v4
	v_mov_b32_e32 v117, v4
	v_mov_b32_e32 v118, v4
	v_mov_b32_e32 v119, v4
	v_mov_b32_e32 v120, v4
	v_mov_b32_e32 v121, v4
	v_mov_b32_e32 v122, v4
	v_mov_b32_e32 v123, v4
	v_mov_b32_e32 v76, v4
	v_mov_b32_e32 v77, v4
	v_mov_b32_e32 v78, v4
	v_mov_b32_e32 v79, v4
	v_mov_b32_e32 v80, v4
	v_mov_b32_e32 v81, v4
	v_mov_b32_e32 v82, v4
	v_mov_b32_e32 v83, v4
	v_mov_b32_e32 v92, v4
	v_mov_b32_e32 v93, v4
	v_mov_b32_e32 v94, v4
	v_mov_b32_e32 v95, v4
	v_mov_b32_e32 v96, v4
	v_mov_b32_e32 v97, v4
	v_mov_b32_e32 v98, v4
	v_mov_b32_e32 v99, v4
	v_mov_b32_e32 v108, v4
	v_mov_b32_e32 v109, v4
	v_mov_b32_e32 v110, v4
	v_mov_b32_e32 v111, v4
	v_mov_b32_e32 v112, v4
	v_mov_b32_e32 v113, v4
	v_mov_b32_e32 v114, v4
	v_mov_b32_e32 v115, v4
	v_mov_b32_e32 v128, v4
	v_mov_b32_e32 v129, v4
	v_mov_b32_e32 v130, v4
	v_mov_b32_e32 v131, v4
	v_mov_b32_e32 v124, v4
	v_mov_b32_e32 v125, v4
	v_mov_b32_e32 v126, v4
	v_mov_b32_e32 v127, v4
	.p2align	6

;     __host__ __device__ bool next(int i, Unit& u) const { const long L = (long)i * G + c; if (L >= (long)nM * nN * nq) return false; const int t = (int)L / nq; u.kq = (int)L % nq; u.pm = t % nM; u.pn = t / nM; return true; }
; template <class Epi, class Sched, bool ALIGN_EPI = false, bool SP2 = false>
; __device__ __forceinline__ void gemm_phase(PG8_LAS unsigned char* lds, const Gemm g, const Sched& S, const Epi& E, int tid_in) {
;     ...
;     for (;;) {
;         const bool has_next = S.next(ui + 1, nxt);
;         const char* nA = has_next ? (const char*)g.A + (size_t)nxt.pm * tsA + (size_t)nxt.kq * g.kqb : cA; const char* nB = has_next ? (const char*)g.Bt + (size_t)nxt.pn * tsB + (size_t)nxt.kq * g.kqb : cB;
;         for (int t = 0; t < nt; t += 2) {
;     ...
; #pragma unroll
;         for (int a = 0; a < 2; ++a)
; #pragma unroll
;             for (int b = 0; b < 2; ++b)
; #pragma unroll
;                 for (int m = 0; m < 4; ++m)
; #pragma unroll
;                     for (int n = 0; n < 2; ++n) acc[a][b][m][n] = (f32x4){0.f, 0.f, 0.f, 0.f};
;         cur = nxt; cA = nA; cB = nB; ++ui;
.LBB0_483:
	v_mov_b32_e32 v127, 0
	s_andn2_b64 vcc, exec, s[16:17]
	v_mov_b32_e32 v126, v127
	v_mov_b32_e32 v125, v127
	v_mov_b32_e32 v124, v127
	v_mov_b32_e32 v131, v127
	v_mov_b32_e32 v130, v127
	v_mov_b32_e32 v129, v127
	v_mov_b32_e32 v128, v127
	v_mov_b32_e32 v115, v127
	v_mov_b32_e32 v114, v127
	v_mov_b32_e32 v113, v127
	v_mov_b32_e32 v112, v127
	v_mov_b32_e32 v111, v127
	v_mov_b32_e32 v110, v127
	v_mov_b32_e32 v109, v127
	v_mov_b32_e32 v108, v127
	v_mov_b32_e32 v99, v127
	v_mov_b32_e32 v98, v127
	v_mov_b32_e32 v97, v127
	v_mov_b32_e32 v96, v127
	v_mov_b32_e32 v95, v127
	v_mov_b32_e32 v94, v127
	v_mov_b32_e32 v93, v127
	v_mov_b32_e32 v92, v127
	v_mov_b32_e32 v83, v127
	v_mov_b32_e32 v82, v127
	v_mov_b32_e32 v81, v127
	v_mov_b32_e32 v80, v127
	v_mov_b32_e32 v79, v127
	v_mov_b32_e32 v78, v127
	v_mov_b32_e32 v77, v127
	v_mov_b32_e32 v76, v127
	v_mov_b32_e32 v123, v127
	v_mov_b32_e32 v122, v127
	v_mov_b32_e32 v121, v127
	v_mov_b32_e32 v120, v127
	v_mov_b32_e32 v119, v127
	v_mov_b32_e32 v118, v127
	v_mov_b32_e32 v117, v127
	v_mov_b32_e32 v116, v127
	v_mov_b32_e32 v107, v127
	v_mov_b32_e32 v106, v127
	v_mov_b32_e32 v105, v127
	v_mov_b32_e32 v104, v127
	v_mov_b32_e32 v103, v127
	v_mov_b32_e32 v102, v127
	v_mov_b32_e32 v101, v127
	v_mov_b32_e32 v100, v127
	v_mov_b32_e32 v91, v127
	v_mov_b32_e32 v90, v127
	v_mov_b32_e32 v89, v127
	v_mov_b32_e32 v88, v127
	v_mov_b32_e32 v87, v127
	v_mov_b32_e32 v86, v127
	v_mov_b32_e32 v85, v127
	v_mov_b32_e32 v84, v127
	v_mov_b32_e32 v75, v127
	v_mov_b32_e32 v74, v127
	v_mov_b32_e32 v73, v127
	v_mov_b32_e32 v72, v127
	v_mov_b32_e32 v71, v127
	v_mov_b32_e32 v70, v127
	v_mov_b32_e32 v69, v127
	v_mov_b32_e32 v68, v127
	v_mov_b32_e32 v67, v127
	v_mov_b32_e32 v66, v127
	v_mov_b32_e32 v65, v127
	v_mov_b32_e32 v64, v127
	v_mov_b32_e32 v63, v127
	v_mov_b32_e32 v62, v127
	v_mov_b32_e32 v61, v127
	v_mov_b32_e32 v60, v127
	v_mov_b32_e32 v51, v127
	v_mov_b32_e32 v50, v127
	v_mov_b32_e32 v49, v127
	v_mov_b32_e32 v48, v127
	v_mov_b32_e32 v47, v127
	v_mov_b32_e32 v46, v127
	v_mov_b32_e32 v45, v127
	v_mov_b32_e32 v44, v127
	v_mov_b32_e32 v35, v127
	v_mov_b32_e32 v34, v127
	v_mov_b32_e32 v33, v127
	v_mov_b32_e32 v32, v127
	v_mov_b32_e32 v31, v127
	v_mov_b32_e32 v30, v127
	v_mov_b32_e32 v29, v127
	v_mov_b32_e32 v28, v127
	v_mov_b32_e32 v19, v127
	v_mov_b32_e32 v18, v127
	v_mov_b32_e32 v17, v127
	v_mov_b32_e32 v16, v127
	v_mov_b32_e32 v15, v127
	v_mov_b32_e32 v14, v127
	v_mov_b32_e32 v13, v127
	v_mov_b32_e32 v12, v127
	v_mov_b32_e32 v59, v127
	v_mov_b32_e32 v58, v127
	v_mov_b32_e32 v57, v127
	v_mov_b32_e32 v56, v127
	v_mov_b32_e32 v55, v127
	v_mov_b32_e32 v54, v127
	v_mov_b32_e32 v53, v127
	v_mov_b32_e32 v52, v127
	v_mov_b32_e32 v43, v127
	v_mov_b32_e32 v42, v127
	v_mov_b32_e32 v41, v127
	v_mov_b32_e32 v40, v127
	v_mov_b32_e32 v39, v127
	v_mov_b32_e32 v38, v127
	v_mov_b32_e32 v37, v127
	v_mov_b32_e32 v36, v127
	v_mov_b32_e32 v27, v127
	v_mov_b32_e32 v26, v127
	v_mov_b32_e32 v25, v127
	v_mov_b32_e32 v24, v127
	v_mov_b32_e32 v23, v127
	v_mov_b32_e32 v22, v127
	v_mov_b32_e32 v21, v127
	v_mov_b32_e32 v20, v127
	v_mov_b32_e32 v11, v127
	v_mov_b32_e32 v10, v127
	v_mov_b32_e32 v9, v127
	v_mov_b32_e32 v8, v127
	v_mov_b32_e32 v7, v127
	v_mov_b32_e32 v6, v127
	v_mov_b32_e32 v5, v127
	v_mov_b32_e32 v4, v127
	s_cbranch_vccnz .LBB0_486
	s_add_u32 s51, s22, 0x100
	s_addc_u32 s52, s23, 0
	s_add_u32 s22, s24, 0x80
	v_mov_b32_e32 v4, 0
	s_addc_u32 s23, s25, 0
	s_mov_b32 s53, 2
	v_mov_b32_e32 v5, v4
	v_mov_b32_e32 v6, v4
	v_mov_b32_e32 v7, v4
	v_mov_b32_e32 v8, v4
	v_mov_b32_e32 v9, v4
	v_mov_b32_e32 v10, v4
	v_mov_b32_e32 v11, v4
	v_mov_b32_e32 v20, v4
	v_mov_b32_e32 v21, v4
	v_mov_b32_e32 v22, v4
	v_mov_b32_e32 v23, v4
	v_mov_b32_e32 v24, v4
	v_mov_b32_e32 v25, v4
	v_mov_b32_e32 v26, v4
	v_mov_b32_e32 v27, v4
	v_mov_b32_e32 v36, v4
	v_mov_b32_e32 v37, v4
	v_mov_b32_e32 v38, v4
	v_mov_b32_e32 v39, v4
	v_mov_b32_e32 v40, v4
	v_mov_b32_e32 v41, v4
	v_mov_b32_e32 v42, v4
	v_mov_b32_e32 v43, v4
	v_mov_b32_e32 v52, v4
	v_mov_b32_e32 v53, v4
	v_mov_b32_e32 v54, v4
	v_mov_b32_e32 v55, v4
	v_mov_b32_e32 v56, v4
	v_mov_b32_e32 v57, v4
	v_mov_b32_e32 v58, v4
	v_mov_b32_e32 v59, v4
	v_mov_b32_e32 v12, v4
	v_mov_b32_e32 v13, v4
	v_mov_b32_e32 v14, v4
	v_mov_b32_e32 v15, v4
	v_mov_b32_e32 v16, v4
	v_mov_b32_e32 v17, v4
	v_mov_b32_e32 v18, v4
	v_mov_b32_e32 v19, v4
	v_mov_b32_e32 v28, v4
	v_mov_b32_e32 v29, v4
	v_mov_b32_e32 v30, v4
	v_mov_b32_e32 v31, v4
	v_mov_b32_e32 v32, v4
	v_mov_b32_e32 v33, v4
	v_mov_b32_e32 v34, v4
	v_mov_b32_e32 v35, v4
	v_mov_b32_e32 v44, v4
	v_mov_b32_e32 v45, v4
	v_mov_b32_e32 v46, v4
	v_mov_b32_e32 v47, v4
	v_mov_b32_e32 v48, v4
	v_mov_b32_e32 v49, v4
	v_mov_b32_e32 v50, v4
	v_mov_b32_e32 v51, v4
	v_mov_b32_e32 v60, v4
	v_mov_b32_e32 v61, v4
	v_mov_b32_e32 v62, v4
	v_mov_b32_e32 v63, v4
	v_mov_b32_e32 v64, v4
	v_mov_b32_e32 v65, v4
	v_mov_b32_e32 v66, v4
	v_mov_b32_e32 v67, v4
	v_mov_b32_e32 v68, v4
	v_mov_b32_e32 v69, v4
	v_mov_b32_e32 v70, v4
	v_mov_b32_e32 v71, v4
	v_mov_b32_e32 v72, v4
	v_mov_b32_e32 v73, v4
	v_mov_b32_e32 v74, v4
	v_mov_b32_e32 v75, v4
	v_mov_b32_e32 v84, v4
	v_mov_b32_e32 v85, v4
	v_mov_b32_e32 v86, v4
	v_mov_b32_e32 v87, v4
	v_mov_b32_e32 v88, v4
	v_mov_b32_e32 v89, v4
	v_mov_b32_e32 v90, v4
	v_mov_b32_e32 v91, v4
	v_mov_b32_e32 v100, v4
	v_mov_b32_e32 v101, v4
	v_mov_b32_e32 v102, v4
	v_mov_b32_e32 v103, v4
	v_mov_b32_e32 v104, v4
	v_mov_b32_e32 v105, v4
	v_mov_b32_e32 v106, v4
	v_mov_b32_e32 v107, v4
	v_mov_b32_e32 v116, v4
	v_mov_b32_e32 v117, v4
	v_mov_b32_e32 v118, v4
	v_mov_b32_e32 v119, v4
	v_mov_b32_e32 v120, v4
	v_mov_b32_e32 v121, v4
	v_mov_b32_e32 v122, v4
	v_mov_b32_e32 v123, v4
	v_mov_b32_e32 v76, v4
	v_mov_b32_e32 v77, v4
	v_mov_b32_e32 v78, v4
	v_mov_b32_e32 v79, v4
	v_mov_b32_e32 v80, v4
	v_mov_b32_e32 v81, v4
	v_mov_b32_e32 v82, v4
	v_mov_b32_e32 v83, v4
	v_mov_b32_e32 v92, v4
	v_mov_b32_e32 v93, v4
	v_mov_b32_e32 v94, v4
	v_mov_b32_e32 v95, v4
	v_mov_b32_e32 v96, v4
	v_mov_b32_e32 v97, v4
	v_mov_b32_e32 v98, v4
	v_mov_b32_e32 v99, v4
	v_mov_b32_e32 v108, v4
	v_mov_b32_e32 v109, v4
	v_mov_b32_e32 v110, v4
	v_mov_b32_e32 v111, v4
	v_mov_b32_e32 v112, v4
	v_mov_b32_e32 v113, v4
	v_mov_b32_e32 v114, v4
	v_mov_b32_e32 v115, v4
	v_mov_b32_e32 v128, v4
	v_mov_b32_e32 v129, v4
	v_mov_b32_e32 v130, v4
	v_mov_b32_e32 v131, v4
	v_mov_b32_e32 v124, v4
	v_mov_b32_e32 v125, v4
	v_mov_b32_e32 v126, v4
	v_mov_b32_e32 v127, v4
	.p2align	6

;     __host__ __device__ bool next(int i, Unit& u) const { const long L = (long)i * G + c; if (L >= (long)nM * nN * nq) return false; const int t = (int)L / nq; u.kq = (int)L % nq; u.pm = t % nM; u.pn = t / nM; return true; }
; template <class Epi, class Sched, bool ALIGN_EPI = false, bool SP2 = false>
; __device__ __forceinline__ void gemm_phase(PG8_LAS unsigned char* lds, const Gemm g, const Sched& S, const Epi& E, int tid_in) {
;     ...
;     for (;;) {
;         const bool has_next = S.next(ui + 1, nxt);
;         const char* nA = has_next ? (const char*)g.A + (size_t)nxt.pm * tsA + (size_t)nxt.kq * g.kqb : cA; const char* nB = has_next ? (const char*)g.Bt + (size_t)nxt.pn * tsB + (size_t)nxt.kq * g.kqb : cB;
;         for (int t = 0; t < nt; t += 2) {
;     ...
; #pragma unroll
;         for (int a = 0; a < 2; ++a)
; #pragma unroll
;             for (int b = 0; b < 2; ++b)
; #pragma unroll
;                 for (int m = 0; m < 4; ++m)
; #pragma unroll
;                     for (int n = 0; n < 2; ++n) acc[a][b][m][n] = (f32x4){0.f, 0.f, 0.f, 0.f};
;         cur = nxt; cA = nA; cB = nB; ++ui;
.LBB0_665:
	v_mov_b32_e32 v143, 0
	s_andn2_b64 vcc, exec, s[18:19]
	v_mov_b32_e32 v142, v143
	v_mov_b32_e32 v141, v143
	v_mov_b32_e32 v140, v143
	v_mov_b32_e32 v147, v143
	v_mov_b32_e32 v146, v143
	v_mov_b32_e32 v145, v143
	v_mov_b32_e32 v144, v143
	v_mov_b32_e32 v131, v143
	v_mov_b32_e32 v130, v143
	v_mov_b32_e32 v129, v143
	v_mov_b32_e32 v128, v143
	v_mov_b32_e32 v127, v143
	v_mov_b32_e32 v126, v143
	v_mov_b32_e32 v125, v143
	v_mov_b32_e32 v124, v143
	v_mov_b32_e32 v115, v143
	v_mov_b32_e32 v114, v143
	v_mov_b32_e32 v113, v143
	v_mov_b32_e32 v112, v143
	v_mov_b32_e32 v111, v143
	v_mov_b32_e32 v110, v143
	v_mov_b32_e32 v109, v143
	v_mov_b32_e32 v108, v143
	v_mov_b32_e32 v99, v143
	v_mov_b32_e32 v98, v143
	v_mov_b32_e32 v97, v143
	v_mov_b32_e32 v96, v143
	v_mov_b32_e32 v95, v143
	v_mov_b32_e32 v94, v143
	v_mov_b32_e32 v93, v143
	v_mov_b32_e32 v92, v143
	v_mov_b32_e32 v139, v143
	v_mov_b32_e32 v138, v143
	v_mov_b32_e32 v137, v143
	v_mov_b32_e32 v136, v143
	v_mov_b32_e32 v135, v143
	v_mov_b32_e32 v134, v143
	v_mov_b32_e32 v133, v143
	v_mov_b32_e32 v132, v143
	v_mov_b32_e32 v123, v143
	v_mov_b32_e32 v122, v143
	v_mov_b32_e32 v121, v143
	v_mov_b32_e32 v120, v143
	v_mov_b32_e32 v119, v143
	v_mov_b32_e32 v118, v143
	v_mov_b32_e32 v117, v143
	v_mov_b32_e32 v116, v143
	v_mov_b32_e32 v107, v143
	v_mov_b32_e32 v106, v143
	v_mov_b32_e32 v105, v143
	v_mov_b32_e32 v104, v143
	v_mov_b32_e32 v103, v143
	v_mov_b32_e32 v102, v143
	v_mov_b32_e32 v101, v143
	v_mov_b32_e32 v100, v143
	v_mov_b32_e32 v91, v143
	v_mov_b32_e32 v90, v143
	v_mov_b32_e32 v89, v143
	v_mov_b32_e32 v88, v143
	v_mov_b32_e32 v87, v143
	v_mov_b32_e32 v86, v143
	v_mov_b32_e32 v85, v143
	v_mov_b32_e32 v84, v143
	v_mov_b32_e32 v83, v143
	v_mov_b32_e32 v82, v143
	v_mov_b32_e32 v81, v143
	v_mov_b32_e32 v80, v143
	v_mov_b32_e32 v79, v143
	v_mov_b32_e32 v78, v143
	v_mov_b32_e32 v77, v143
	v_mov_b32_e32 v76, v143
	v_mov_b32_e32 v67, v143
	v_mov_b32_e32 v66, v143
	v_mov_b32_e32 v65, v143
	v_mov_b32_e32 v64, v143
	v_mov_b32_e32 v63, v143
	v_mov_b32_e32 v62, v143
	v_mov_b32_e32 v61, v143
	v_mov_b32_e32 v60, v143
	v_mov_b32_e32 v43, v143
	v_mov_b32_e32 v42, v143
	v_mov_b32_e32 v41, v143
	v_mov_b32_e32 v40, v143
	v_mov_b32_e32 v39, v143
	v_mov_b32_e32 v38, v143
	v_mov_b32_e32 v37, v143
	v_mov_b32_e32 v36, v143
	v_mov_b32_e32 v19, v143
	v_mov_b32_e32 v18, v143
	v_mov_b32_e32 v17, v143
	v_mov_b32_e32 v16, v143
	v_mov_b32_e32 v15, v143
	v_mov_b32_e32 v14, v143
	v_mov_b32_e32 v13, v143
	v_mov_b32_e32 v12, v143
	v_mov_b32_e32 v75, v143
	v_mov_b32_e32 v74, v143
	v_mov_b32_e32 v73, v143
	v_mov_b32_e32 v72, v143
	v_mov_b32_e32 v71, v143
	v_mov_b32_e32 v70, v143
	v_mov_b32_e32 v69, v143
	v_mov_b32_e32 v68, v143
	v_mov_b32_e32 v59, v143
	v_mov_b32_e32 v58, v143
	v_mov_b32_e32 v57, v143
	v_mov_b32_e32 v56, v143
	v_mov_b32_e32 v55, v143
	v_mov_b32_e32 v54, v143
	v_mov_b32_e32 v53, v143
	v_mov_b32_e32 v52, v143
	v_mov_b32_e32 v27, v143
	v_mov_b32_e32 v26, v143
	v_mov_b32_e32 v25, v143
	v_mov_b32_e32 v24, v143
	v_mov_b32_e32 v23, v143
	v_mov_b32_e32 v22, v143
	v_mov_b32_e32 v21, v143
	v_mov_b32_e32 v20, v143
	v_mov_b32_e32 v11, v143
	v_mov_b32_e32 v10, v143
	v_mov_b32_e32 v9, v143
	v_mov_b32_e32 v8, v143
	v_mov_b32_e32 v7, v143
	v_mov_b32_e32 v6, v143
	v_mov_b32_e32 v5, v143
	v_mov_b32_e32 v4, v143
	s_cbranch_vccnz .LBB0_668
	s_add_u32 s53, s22, 0x100
	s_addc_u32 s54, s23, 0
	s_add_u32 s22, s24, 0x80
	v_mov_b32_e32 v4, 0
	s_addc_u32 s23, s25, 0
	s_mov_b32 s55, 2
	v_mov_b32_e32 v5, v4
	v_mov_b32_e32 v6, v4
	v_mov_b32_e32 v7, v4
	v_mov_b32_e32 v8, v4
	v_mov_b32_e32 v9, v4
	v_mov_b32_e32 v10, v4
	v_mov_b32_e32 v11, v4
	v_mov_b32_e32 v20, v4
	v_mov_b32_e32 v21, v4
	v_mov_b32_e32 v22, v4
	v_mov_b32_e32 v23, v4
	v_mov_b32_e32 v24, v4
	v_mov_b32_e32 v25, v4
	v_mov_b32_e32 v26, v4
	v_mov_b32_e32 v27, v4
	v_mov_b32_e32 v52, v4
	v_mov_b32_e32 v53, v4
	v_mov_b32_e32 v54, v4
	v_mov_b32_e32 v55, v4
	v_mov_b32_e32 v56, v4
	v_mov_b32_e32 v57, v4
	v_mov_b32_e32 v58, v4
	v_mov_b32_e32 v59, v4
	v_mov_b32_e32 v68, v4
	v_mov_b32_e32 v69, v4
	v_mov_b32_e32 v70, v4
	v_mov_b32_e32 v71, v4
	v_mov_b32_e32 v72, v4
	v_mov_b32_e32 v73, v4
	v_mov_b32_e32 v74, v4
	v_mov_b32_e32 v75, v4
	v_mov_b32_e32 v12, v4
	v_mov_b32_e32 v13, v4
	v_mov_b32_e32 v14, v4
	v_mov_b32_e32 v15, v4
	v_mov_b32_e32 v16, v4
	v_mov_b32_e32 v17, v4
	v_mov_b32_e32 v18, v4
	v_mov_b32_e32 v19, v4
	v_mov_b32_e32 v36, v4
	v_mov_b32_e32 v37, v4
	v_mov_b32_e32 v38, v4
	v_mov_b32_e32 v39, v4
	v_mov_b32_e32 v40, v4
	v_mov_b32_e32 v41, v4
	v_mov_b32_e32 v42, v4
	v_mov_b32_e32 v43, v4
	v_mov_b32_e32 v60, v4
	v_mov_b32_e32 v61, v4
	v_mov_b32_e32 v62, v4
	v_mov_b32_e32 v63, v4
	v_mov_b32_e32 v64, v4
	v_mov_b32_e32 v65, v4
	v_mov_b32_e32 v66, v4
	v_mov_b32_e32 v67, v4
	v_mov_b32_e32 v76, v4
	v_mov_b32_e32 v77, v4
	v_mov_b32_e32 v78, v4
	v_mov_b32_e32 v79, v4
	v_mov_b32_e32 v80, v4
	v_mov_b32_e32 v81, v4
	v_mov_b32_e32 v82, v4
	v_mov_b32_e32 v83, v4
	v_mov_b32_e32 v84, v4
	v_mov_b32_e32 v85, v4
	v_mov_b32_e32 v86, v4
	v_mov_b32_e32 v87, v4
	v_mov_b32_e32 v88, v4
	v_mov_b32_e32 v89, v4
	v_mov_b32_e32 v90, v4
	v_mov_b32_e32 v91, v4
	v_mov_b32_e32 v100, v4
	v_mov_b32_e32 v101, v4
	v_mov_b32_e32 v102, v4
	v_mov_b32_e32 v103, v4
	v_mov_b32_e32 v104, v4
	v_mov_b32_e32 v105, v4
	v_mov_b32_e32 v106, v4
	v_mov_b32_e32 v107, v4
	v_mov_b32_e32 v116, v4
	v_mov_b32_e32 v117, v4
	v_mov_b32_e32 v118, v4
	v_mov_b32_e32 v119, v4
	v_mov_b32_e32 v120, v4
	v_mov_b32_e32 v121, v4
	v_mov_b32_e32 v122, v4
	v_mov_b32_e32 v123, v4
	v_mov_b32_e32 v132, v4
	v_mov_b32_e32 v133, v4
	v_mov_b32_e32 v134, v4
	v_mov_b32_e32 v135, v4
	v_mov_b32_e32 v136, v4
	v_mov_b32_e32 v137, v4
	v_mov_b32_e32 v138, v4
	v_mov_b32_e32 v139, v4
	v_mov_b32_e32 v92, v4
	v_mov_b32_e32 v93, v4
	v_mov_b32_e32 v94, v4
	v_mov_b32_e32 v95, v4
	v_mov_b32_e32 v96, v4
	v_mov_b32_e32 v97, v4
	v_mov_b32_e32 v98, v4
	v_mov_b32_e32 v99, v4
	v_mov_b32_e32 v108, v4
	v_mov_b32_e32 v109, v4
	v_mov_b32_e32 v110, v4
	v_mov_b32_e32 v111, v4
	v_mov_b32_e32 v112, v4
	v_mov_b32_e32 v113, v4
	v_mov_b32_e32 v114, v4
	v_mov_b32_e32 v115, v4
	v_mov_b32_e32 v124, v4
	v_mov_b32_e32 v125, v4
	v_mov_b32_e32 v126, v4
	v_mov_b32_e32 v127, v4
	v_mov_b32_e32 v128, v4
	v_mov_b32_e32 v129, v4
	v_mov_b32_e32 v130, v4
	v_mov_b32_e32 v131, v4
	v_mov_b32_e32 v144, v4
	v_mov_b32_e32 v145, v4
	v_mov_b32_e32 v146, v4
	v_mov_b32_e32 v147, v4
	v_mov_b32_e32 v140, v4
	v_mov_b32_e32 v141, v4
	v_mov_b32_e32 v142, v4
	v_mov_b32_e32 v143, v4
	.p2align	6

; template <class Epi, class Sched, bool ALIGN_EPI = false, bool SP2 = false>
; __device__ __forceinline__ void gemm_phase(PG8_LAS unsigned char* lds, const Gemm g, const Sched& S, const Epi& E, int tid_in) {
;     ...
;         for (int t = 0; t < nt; t += 2) {
;             const bool last = (t == nt - 2);
;             if constexpr (mid_hook<Epi>::value) { if (t == Epi::H1 || t == Epi::H2) E.mid(acc, cur, wr, wc, fr, fq, t == Epi::H2); }
;             const char* a1 = cA + (size_t)(t + 1) * kstep + (t >= jt ? jb : 0);
;             const char* a2 = last ? nA : cA + (size_t)(t + 2) * kstep + (t + 2 >= jt ? jb : 0); const char* b2 = last ? nB : cB + (size_t)(t + 2) * kstep;
;             const char* a3 = a2 + kstep; const char* b3 = b2 + kstep;
;     ...
; #pragma unroll
;         for (int a = 0; a < 2; ++a)
; #pragma unroll
;             for (int b = 0; b < 2; ++b)
; #pragma unroll
;                 for (int m = 0; m < 4; ++m)
; #pragma unroll
;                     for (int n = 0; n < 2; ++n) acc[a][b][m][n] = (f32x4){0.f, 0.f, 0.f, 0.f};
;         cur = nxt; cA = nA; cB = nB; ++ui;
.LBB0_686:
	v_mov_b32_e32 v143, 0
	s_andn2_b64 vcc, exec, s[16:17]
	v_mov_b32_e32 v142, v143
	v_mov_b32_e32 v141, v143
	v_mov_b32_e32 v140, v143
	v_mov_b32_e32 v147, v143
	v_mov_b32_e32 v146, v143
	v_mov_b32_e32 v145, v143
	v_mov_b32_e32 v144, v143
	v_mov_b32_e32 v131, v143
	v_mov_b32_e32 v130, v143
	v_mov_b32_e32 v129, v143
	v_mov_b32_e32 v128, v143
	v_mov_b32_e32 v127, v143
	v_mov_b32_e32 v126, v143
	v_mov_b32_e32 v125, v143
	v_mov_b32_e32 v124, v143
	v_mov_b32_e32 v115, v143
	v_mov_b32_e32 v114, v143
	v_mov_b32_e32 v113, v143
	v_mov_b32_e32 v112, v143
	v_mov_b32_e32 v111, v143
	v_mov_b32_e32 v110, v143
	v_mov_b32_e32 v109, v143
	v_mov_b32_e32 v108, v143
	v_mov_b32_e32 v99, v143
	v_mov_b32_e32 v98, v143
	v_mov_b32_e32 v97, v143
	v_mov_b32_e32 v96, v143
	v_mov_b32_e32 v95, v143
	v_mov_b32_e32 v94, v143
	v_mov_b32_e32 v93, v143
	v_mov_b32_e32 v92, v143
	v_mov_b32_e32 v139, v143
	v_mov_b32_e32 v138, v143
	v_mov_b32_e32 v137, v143
	v_mov_b32_e32 v136, v143
	v_mov_b32_e32 v135, v143
	v_mov_b32_e32 v134, v143
	v_mov_b32_e32 v133, v143
	v_mov_b32_e32 v132, v143
	v_mov_b32_e32 v123, v143
	v_mov_b32_e32 v122, v143
	v_mov_b32_e32 v121, v143
	v_mov_b32_e32 v120, v143
	v_mov_b32_e32 v119, v143
	v_mov_b32_e32 v118, v143
	v_mov_b32_e32 v117, v143
	v_mov_b32_e32 v116, v143
	v_mov_b32_e32 v107, v143
	v_mov_b32_e32 v106, v143
	v_mov_b32_e32 v105, v143
	v_mov_b32_e32 v104, v143
	v_mov_b32_e32 v103, v143
	v_mov_b32_e32 v102, v143
	v_mov_b32_e32 v101, v143
	v_mov_b32_e32 v100, v143
	v_mov_b32_e32 v83, v143
	v_mov_b32_e32 v82, v143
	v_mov_b32_e32 v81, v143
	v_mov_b32_e32 v80, v143
	v_mov_b32_e32 v79, v143
	v_mov_b32_e32 v78, v143
	v_mov_b32_e32 v77, v143
	v_mov_b32_e32 v76, v143
	v_mov_b32_e32 v67, v143
	v_mov_b32_e32 v66, v143
	v_mov_b32_e32 v65, v143
	v_mov_b32_e32 v64, v143
	v_mov_b32_e32 v63, v143
	v_mov_b32_e32 v62, v143
	v_mov_b32_e32 v61, v143
	v_mov_b32_e32 v60, v143
	v_mov_b32_e32 v51, v143
	v_mov_b32_e32 v50, v143
	v_mov_b32_e32 v49, v143
	v_mov_b32_e32 v48, v143
	v_mov_b32_e32 v47, v143
	v_mov_b32_e32 v46, v143
	v_mov_b32_e32 v45, v143
	v_mov_b32_e32 v44, v143
	v_mov_b32_e32 v35, v143
	v_mov_b32_e32 v34, v143
	v_mov_b32_e32 v33, v143
	v_mov_b32_e32 v32, v143
	v_mov_b32_e32 v31, v143
	v_mov_b32_e32 v30, v143
	v_mov_b32_e32 v29, v143
	v_mov_b32_e32 v28, v143
	v_mov_b32_e32 v19, v143
	v_mov_b32_e32 v18, v143
	v_mov_b32_e32 v17, v143
	v_mov_b32_e32 v16, v143
	v_mov_b32_e32 v15, v143
	v_mov_b32_e32 v14, v143
	v_mov_b32_e32 v13, v143
	v_mov_b32_e32 v12, v143
	v_mov_b32_e32 v59, v143
	v_mov_b32_e32 v58, v143
	v_mov_b32_e32 v57, v143
	v_mov_b32_e32 v56, v143
	v_mov_b32_e32 v55, v143
	v_mov_b32_e32 v54, v143
	v_mov_b32_e32 v53, v143
	v_mov_b32_e32 v52, v143
	v_mov_b32_e32 v43, v143
	v_mov_b32_e32 v42, v143
	v_mov_b32_e32 v41, v143
	v_mov_b32_e32 v40, v143
	v_mov_b32_e32 v39, v143
	v_mov_b32_e32 v38, v143
	v_mov_b32_e32 v37, v143
	v_mov_b32_e32 v36, v143
	v_mov_b32_e32 v27, v143
	v_mov_b32_e32 v26, v143
	v_mov_b32_e32 v25, v143
	v_mov_b32_e32 v24, v143
	v_mov_b32_e32 v23, v143
	v_mov_b32_e32 v22, v143
	v_mov_b32_e32 v21, v143
	v_mov_b32_e32 v20, v143
	v_mov_b32_e32 v11, v143
	v_mov_b32_e32 v10, v143
	v_mov_b32_e32 v9, v143
	v_mov_b32_e32 v8, v143
	v_mov_b32_e32 v7, v143
	v_mov_b32_e32 v6, v143
	v_mov_b32_e32 v5, v143
	v_mov_b32_e32 v4, v143
	s_cbranch_vccnz .LBB0_689
	s_add_u32 s53, s22, 0x100
	s_addc_u32 s54, s23, 0
	s_add_u32 s22, s24, 0x80
	v_mov_b32_e32 v4, 0
	s_addc_u32 s23, s25, 0
	s_mov_b32 s55, 2
	v_mov_b32_e32 v5, v4
	v_mov_b32_e32 v6, v4
	v_mov_b32_e32 v7, v4
	v_mov_b32_e32 v8, v4
	v_mov_b32_e32 v9, v4
	v_mov_b32_e32 v10, v4
	v_mov_b32_e32 v11, v4
	v_mov_b32_e32 v20, v4
	v_mov_b32_e32 v21, v4
	v_mov_b32_e32 v22, v4
	v_mov_b32_e32 v23, v4
	v_mov_b32_e32 v24, v4
	v_mov_b32_e32 v25, v4
	v_mov_b32_e32 v26, v4
	v_mov_b32_e32 v27, v4
	v_mov_b32_e32 v36, v4
	v_mov_b32_e32 v37, v4
	v_mov_b32_e32 v38, v4
	v_mov_b32_e32 v39, v4
	v_mov_b32_e32 v40, v4
	v_mov_b32_e32 v41, v4
	v_mov_b32_e32 v42, v4
	v_mov_b32_e32 v43, v4
	v_mov_b32_e32 v52, v4
	v_mov_b32_e32 v53, v4
	v_mov_b32_e32 v54, v4
	v_mov_b32_e32 v55, v4
	v_mov_b32_e32 v56, v4
	v_mov_b32_e32 v57, v4
	v_mov_b32_e32 v58, v4
	v_mov_b32_e32 v59, v4
	v_mov_b32_e32 v12, v4
	v_mov_b32_e32 v13, v4
	v_mov_b32_e32 v14, v4
	v_mov_b32_e32 v15, v4
	v_mov_b32_e32 v16, v4
	v_mov_b32_e32 v17, v4
	v_mov_b32_e32 v18, v4
	v_mov_b32_e32 v19, v4
	v_mov_b32_e32 v28, v4
	v_mov_b32_e32 v29, v4
	v_mov_b32_e32 v30, v4
	v_mov_b32_e32 v31, v4
	v_mov_b32_e32 v32, v4
	v_mov_b32_e32 v33, v4
	v_mov_b32_e32 v34, v4
	v_mov_b32_e32 v35, v4
	v_mov_b32_e32 v44, v4
	v_mov_b32_e32 v45, v4
	v_mov_b32_e32 v46, v4
	v_mov_b32_e32 v47, v4
	v_mov_b32_e32 v48, v4
	v_mov_b32_e32 v49, v4
	v_mov_b32_e32 v50, v4
	v_mov_b32_e32 v51, v4
	v_mov_b32_e32 v60, v4
	v_mov_b32_e32 v61, v4
	v_mov_b32_e32 v62, v4
	v_mov_b32_e32 v63, v4
	v_mov_b32_e32 v64, v4
	v_mov_b32_e32 v65, v4
	v_mov_b32_e32 v66, v4
	v_mov_b32_e32 v67, v4
	v_mov_b32_e32 v76, v4
	v_mov_b32_e32 v77, v4
	v_mov_b32_e32 v78, v4
	v_mov_b32_e32 v79, v4
	v_mov_b32_e32 v80, v4
	v_mov_b32_e32 v81, v4
	v_mov_b32_e32 v82, v4
	v_mov_b32_e32 v83, v4
	v_mov_b32_e32 v100, v4
	v_mov_b32_e32 v101, v4
	v_mov_b32_e32 v102, v4
	v_mov_b32_e32 v103, v4
	v_mov_b32_e32 v104, v4
	v_mov_b32_e32 v105, v4
	v_mov_b32_e32 v106, v4
	v_mov_b32_e32 v107, v4
	v_mov_b32_e32 v116, v4
	v_mov_b32_e32 v117, v4
	v_mov_b32_e32 v118, v4
	v_mov_b32_e32 v119, v4
	v_mov_b32_e32 v120, v4
	v_mov_b32_e32 v121, v4
	v_mov_b32_e32 v122, v4
	v_mov_b32_e32 v123, v4
	v_mov_b32_e32 v132, v4
	v_mov_b32_e32 v133, v4
	v_mov_b32_e32 v134, v4
	v_mov_b32_e32 v135, v4
	v_mov_b32_e32 v136, v4
	v_mov_b32_e32 v137, v4
	v_mov_b32_e32 v138, v4
	v_mov_b32_e32 v139, v4
	v_mov_b32_e32 v92, v4
	v_mov_b32_e32 v93, v4
	v_mov_b32_e32 v94, v4
	v_mov_b32_e32 v95, v4
	v_mov_b32_e32 v96, v4
	v_mov_b32_e32 v97, v4
	v_mov_b32_e32 v98, v4
	v_mov_b32_e32 v99, v4
	v_mov_b32_e32 v108, v4
	v_mov_b32_e32 v109, v4
	v_mov_b32_e32 v110, v4
	v_mov_b32_e32 v111, v4
	v_mov_b32_e32 v112, v4
	v_mov_b32_e32 v113, v4
	v_mov_b32_e32 v114, v4
	v_mov_b32_e32 v115, v4
	v_mov_b32_e32 v124, v4
	v_mov_b32_e32 v125, v4
	v_mov_b32_e32 v126, v4
	v_mov_b32_e32 v127, v4
	v_mov_b32_e32 v128, v4
	v_mov_b32_e32 v129, v4
	v_mov_b32_e32 v130, v4
	v_mov_b32_e32 v131, v4
	v_mov_b32_e32 v144, v4
	v_mov_b32_e32 v145, v4
	v_mov_b32_e32 v146, v4
	v_mov_b32_e32 v147, v4
	v_mov_b32_e32 v140, v4
	v_mov_b32_e32 v141, v4
	v_mov_b32_e32 v142, v4
	v_mov_b32_e32 v143, v4
	.p2align	6

; template <class Epi, class Sched, bool ALIGN_EPI = false, bool SP2 = false>
; __device__ __forceinline__ void gemm_phase(PG8_LAS unsigned char* lds, const Gemm g, const Sched& S, const Epi& E, int tid_in) {
;     ...
;         for (int t = 0; t < nt; t += 2) {
;             const bool last = (t == nt - 2);
;             if constexpr (mid_hook<Epi>::value) { if (t == Epi::H1 || t == Epi::H2) E.mid(acc, cur, wr, wc, fr, fq, t == Epi::H2); }
;             const char* a1 = cA + (size_t)(t + 1) * kstep + (t >= jt ? jb : 0);
;             const char* a2 = last ? nA : cA + (size_t)(t + 2) * kstep + (t + 2 >= jt ? jb : 0); const char* b2 = last ? nB : cB + (size_t)(t + 2) * kstep;
;             const char* a3 = a2 + kstep; const char* b3 = b2 + kstep;
;     ...
; #pragma unroll
;         for (int a = 0; a < 2; ++a)
; #pragma unroll
;             for (int b = 0; b < 2; ++b)
; #pragma unroll
;                 for (int m = 0; m < 4; ++m)
; #pragma unroll
;                     for (int n = 0; n < 2; ++n) acc[a][b][m][n] = (f32x4){0.f, 0.f, 0.f, 0.f};
;         cur = nxt; cA = nA; cB = nB; ++ui;
.LBB0_922:
	v_mov_b32_e32 v131, 0
	s_andn2_b64 vcc, exec, s[16:17]
	v_mov_b32_e32 v130, v131
	v_mov_b32_e32 v129, v131
	v_mov_b32_e32 v128, v131
	v_mov_b32_e32 v127, v131
	v_mov_b32_e32 v126, v131
	v_mov_b32_e32 v125, v131
	v_mov_b32_e32 v124, v131
	v_mov_b32_e32 v115, v131
	v_mov_b32_e32 v114, v131
	v_mov_b32_e32 v113, v131
	v_mov_b32_e32 v112, v131
	v_mov_b32_e32 v111, v131
	v_mov_b32_e32 v110, v131
	v_mov_b32_e32 v109, v131
	v_mov_b32_e32 v108, v131
	v_mov_b32_e32 v99, v131
	v_mov_b32_e32 v98, v131
	v_mov_b32_e32 v97, v131
	v_mov_b32_e32 v96, v131
	v_mov_b32_e32 v95, v131
	v_mov_b32_e32 v94, v131
	v_mov_b32_e32 v93, v131
	v_mov_b32_e32 v92, v131
	v_mov_b32_e32 v83, v131
	v_mov_b32_e32 v82, v131
	v_mov_b32_e32 v81, v131
	v_mov_b32_e32 v80, v131
	v_mov_b32_e32 v79, v131
	v_mov_b32_e32 v78, v131
	v_mov_b32_e32 v77, v131
	v_mov_b32_e32 v76, v131
	v_mov_b32_e32 v123, v131
	v_mov_b32_e32 v122, v131
	v_mov_b32_e32 v121, v131
	v_mov_b32_e32 v120, v131
	v_mov_b32_e32 v119, v131
	v_mov_b32_e32 v118, v131
	v_mov_b32_e32 v117, v131
	v_mov_b32_e32 v116, v131
	v_mov_b32_e32 v107, v131
	v_mov_b32_e32 v106, v131
	v_mov_b32_e32 v105, v131
	v_mov_b32_e32 v104, v131
	v_mov_b32_e32 v103, v131
	v_mov_b32_e32 v102, v131
	v_mov_b32_e32 v101, v131
	v_mov_b32_e32 v100, v131
	v_mov_b32_e32 v91, v131
	v_mov_b32_e32 v90, v131
	v_mov_b32_e32 v89, v131
	v_mov_b32_e32 v88, v131
	v_mov_b32_e32 v87, v131
	v_mov_b32_e32 v86, v131
	v_mov_b32_e32 v85, v131
	v_mov_b32_e32 v84, v131
	v_mov_b32_e32 v75, v131
	v_mov_b32_e32 v74, v131
	v_mov_b32_e32 v73, v131
	v_mov_b32_e32 v72, v131
	v_mov_b32_e32 v71, v131
	v_mov_b32_e32 v70, v131
	v_mov_b32_e32 v69, v131
	v_mov_b32_e32 v68, v131
	v_mov_b32_e32 v67, v131
	v_mov_b32_e32 v66, v131
	v_mov_b32_e32 v65, v131
	v_mov_b32_e32 v64, v131
	v_mov_b32_e32 v63, v131
	v_mov_b32_e32 v62, v131
	v_mov_b32_e32 v61, v131
	v_mov_b32_e32 v60, v131
	v_mov_b32_e32 v51, v131
	v_mov_b32_e32 v50, v131
	v_mov_b32_e32 v49, v131
	v_mov_b32_e32 v48, v131
	v_mov_b32_e32 v47, v131
	v_mov_b32_e32 v46, v131
	v_mov_b32_e32 v45, v131
	v_mov_b32_e32 v44, v131
	v_mov_b32_e32 v35, v131
	v_mov_b32_e32 v34, v131
	v_mov_b32_e32 v33, v131
	v_mov_b32_e32 v32, v131
	v_mov_b32_e32 v31, v131
	v_mov_b32_e32 v30, v131
	v_mov_b32_e32 v29, v131
	v_mov_b32_e32 v28, v131
	v_mov_b32_e32 v19, v131
	v_mov_b32_e32 v18, v131
	v_mov_b32_e32 v17, v131
	v_mov_b32_e32 v16, v131
	v_mov_b32_e32 v15, v131
	v_mov_b32_e32 v14, v131
	v_mov_b32_e32 v13, v131
	v_mov_b32_e32 v12, v131
	v_mov_b32_e32 v59, v131
	v_mov_b32_e32 v58, v131
	v_mov_b32_e32 v57, v131
	v_mov_b32_e32 v56, v131
	v_mov_b32_e32 v55, v131
	v_mov_b32_e32 v54, v131
	v_mov_b32_e32 v53, v131
	v_mov_b32_e32 v52, v131
	v_mov_b32_e32 v43, v131
	v_mov_b32_e32 v42, v131
	v_mov_b32_e32 v41, v131
	v_mov_b32_e32 v40, v131
	v_mov_b32_e32 v39, v131
	v_mov_b32_e32 v38, v131
	v_mov_b32_e32 v37, v131
	v_mov_b32_e32 v36, v131
	v_mov_b32_e32 v27, v131
	v_mov_b32_e32 v26, v131
	v_mov_b32_e32 v25, v131
	v_mov_b32_e32 v24, v131
	v_mov_b32_e32 v23, v131
	v_mov_b32_e32 v22, v131
	v_mov_b32_e32 v21, v131
	v_mov_b32_e32 v20, v131
	v_mov_b32_e32 v11, v131
	v_mov_b32_e32 v10, v131
	v_mov_b32_e32 v9, v131
	v_mov_b32_e32 v8, v131
	v_mov_b32_e32 v7, v131
	v_mov_b32_e32 v6, v131
	v_mov_b32_e32 v5, v131
	v_mov_b32_e32 v4, v131
	s_cbranch_vccnz .LBB0_925
	s_add_u32 s54, s22, 0x100
	s_addc_u32 s55, s23, 0
	s_add_u32 s22, s24, 0x80
	v_mov_b32_e32 v4, 0
	s_addc_u32 s23, s25, 0
	s_mov_b32 s58, 2
	v_mov_b32_e32 v5, v4
	v_mov_b32_e32 v6, v4
	v_mov_b32_e32 v7, v4
	v_mov_b32_e32 v8, v4
	v_mov_b32_e32 v9, v4
	v_mov_b32_e32 v10, v4
	v_mov_b32_e32 v11, v4
	v_mov_b32_e32 v20, v4
	v_mov_b32_e32 v21, v4
	v_mov_b32_e32 v22, v4
	v_mov_b32_e32 v23, v4
	v_mov_b32_e32 v24, v4
	v_mov_b32_e32 v25, v4
	v_mov_b32_e32 v26, v4
	v_mov_b32_e32 v27, v4
	v_mov_b32_e32 v36, v4
	v_mov_b32_e32 v37, v4
	v_mov_b32_e32 v38, v4
	v_mov_b32_e32 v39, v4
	v_mov_b32_e32 v40, v4
	v_mov_b32_e32 v41, v4
	v_mov_b32_e32 v42, v4
	v_mov_b32_e32 v43, v4
	v_mov_b32_e32 v52, v4
	v_mov_b32_e32 v53, v4
	v_mov_b32_e32 v54, v4
	v_mov_b32_e32 v55, v4
	v_mov_b32_e32 v56, v4
	v_mov_b32_e32 v57, v4
	v_mov_b32_e32 v58, v4
	v_mov_b32_e32 v59, v4
	v_mov_b32_e32 v12, v4
	v_mov_b32_e32 v13, v4
	v_mov_b32_e32 v14, v4
	v_mov_b32_e32 v15, v4
	v_mov_b32_e32 v16, v4
	v_mov_b32_e32 v17, v4
	v_mov_b32_e32 v18, v4
	v_mov_b32_e32 v19, v4
	v_mov_b32_e32 v28, v4
	v_mov_b32_e32 v29, v4
	v_mov_b32_e32 v30, v4
	v_mov_b32_e32 v31, v4
	v_mov_b32_e32 v32, v4
	v_mov_b32_e32 v33, v4
	v_mov_b32_e32 v34, v4
	v_mov_b32_e32 v35, v4
	v_mov_b32_e32 v44, v4
	v_mov_b32_e32 v45, v4
	v_mov_b32_e32 v46, v4
	v_mov_b32_e32 v47, v4
	v_mov_b32_e32 v48, v4
	v_mov_b32_e32 v49, v4
	v_mov_b32_e32 v50, v4
	v_mov_b32_e32 v51, v4
	v_mov_b32_e32 v60, v4
	v_mov_b32_e32 v61, v4
	v_mov_b32_e32 v62, v4
	v_mov_b32_e32 v63, v4
	v_mov_b32_e32 v64, v4
	v_mov_b32_e32 v65, v4
	v_mov_b32_e32 v66, v4
	v_mov_b32_e32 v67, v4
	v_mov_b32_e32 v68, v4
	v_mov_b32_e32 v69, v4
	v_mov_b32_e32 v70, v4
	v_mov_b32_e32 v71, v4
	v_mov_b32_e32 v72, v4
	v_mov_b32_e32 v73, v4
	v_mov_b32_e32 v74, v4
	v_mov_b32_e32 v75, v4
	v_mov_b32_e32 v84, v4
	v_mov_b32_e32 v85, v4
	v_mov_b32_e32 v86, v4
	v_mov_b32_e32 v87, v4
	v_mov_b32_e32 v88, v4
	v_mov_b32_e32 v89, v4
	v_mov_b32_e32 v90, v4
	v_mov_b32_e32 v91, v4
	v_mov_b32_e32 v100, v4
	v_mov_b32_e32 v101, v4
	v_mov_b32_e32 v102, v4
	v_mov_b32_e32 v103, v4
	v_mov_b32_e32 v104, v4
	v_mov_b32_e32 v105, v4
	v_mov_b32_e32 v106, v4
	v_mov_b32_e32 v107, v4
	v_mov_b32_e32 v116, v4
	v_mov_b32_e32 v117, v4
	v_mov_b32_e32 v118, v4
	v_mov_b32_e32 v119, v4
	v_mov_b32_e32 v120, v4
	v_mov_b32_e32 v121, v4
	v_mov_b32_e32 v122, v4
	v_mov_b32_e32 v123, v4
	v_mov_b32_e32 v76, v4
	v_mov_b32_e32 v77, v4
	v_mov_b32_e32 v78, v4
	v_mov_b32_e32 v79, v4
	v_mov_b32_e32 v80, v4
	v_mov_b32_e32 v81, v4
	v_mov_b32_e32 v82, v4
	v_mov_b32_e32 v83, v4
	v_mov_b32_e32 v92, v4
	v_mov_b32_e32 v93, v4
	v_mov_b32_e32 v94, v4
	v_mov_b32_e32 v95, v4
	v_mov_b32_e32 v96, v4
	v_mov_b32_e32 v97, v4
	v_mov_b32_e32 v98, v4
	v_mov_b32_e32 v99, v4
	v_mov_b32_e32 v108, v4
	v_mov_b32_e32 v109, v4
	v_mov_b32_e32 v110, v4
	v_mov_b32_e32 v111, v4
	v_mov_b32_e32 v112, v4
	v_mov_b32_e32 v113, v4
	v_mov_b32_e32 v114, v4
	v_mov_b32_e32 v115, v4
	v_mov_b32_e32 v124, v4
	v_mov_b32_e32 v125, v4
	v_mov_b32_e32 v126, v4
	v_mov_b32_e32 v127, v4
	v_mov_b32_e32 v128, v4
	v_mov_b32_e32 v129, v4
	v_mov_b32_e32 v130, v4
	v_mov_b32_e32 v131, v4
	.p2align	6

; template <class Epi, class Sched, bool ALIGN_EPI = false, bool SP2 = false>
; __device__ __forceinline__ void gemm_phase(PG8_LAS unsigned char* lds, const Gemm g, const Sched& S, const Epi& E, int tid_in) {
;     ...
;         for (int t = 0; t < nt; t += 2) {
;             const bool last = (t == nt - 2);
;             if constexpr (mid_hook<Epi>::value) { if (t == Epi::H1 || t == Epi::H2) E.mid(acc, cur, wr, wc, fr, fq, t == Epi::H2); }
.LBB0_989:
	s_cmp_eq_u32 s62, 32
	s_cselect_b64 s[28:29], -1, 0
	s_cbranch_execz .LBB0_991
	s_branch .LBB0_992
	.p2align	6

; template <class Epi, class Sched, bool ALIGN_EPI = false, bool SP2 = false>
; __device__ __forceinline__ void gemm_phase(PG8_LAS unsigned char* lds, const Gemm g, const Sched& S, const Epi& E, int tid_in) {
;     ...
;         for (int t = 0; t < nt; t += 2) {
;             const bool last = (t == nt - 2);
;             if constexpr (mid_hook<Epi>::value) { if (t == Epi::H1 || t == Epi::H2) E.mid(acc, cur, wr, wc, fr, fq, t == Epi::H2); }
;             const char* a1 = cA + (size_t)(t + 1) * kstep + (t >= jt ? jb : 0);
;             const char* a2 = last ? nA : cA + (size_t)(t + 2) * kstep + (t + 2 >= jt ? jb : 0); const char* b2 = last ? nB : cB + (size_t)(t + 2) * kstep;
;             const char* a3 = a2 + kstep; const char* b3 = b2 + kstep;
;     ...
; #pragma unroll
;         for (int a = 0; a < 2; ++a)
; #pragma unroll
;             for (int b = 0; b < 2; ++b)
; #pragma unroll
;                 for (int m = 0; m < 4; ++m)
; #pragma unroll
;                     for (int n = 0; n < 2; ++n) acc[a][b][m][n] = (f32x4){0.f, 0.f, 0.f, 0.f};
;         cur = nxt; cA = nA; cB = nB; ++ui;
.LBB0_1068:
	v_mov_b32_e32 v139, 0
	s_andn2_b64 vcc, exec, s[22:23]
	v_mov_b32_e32 v138, v139
	v_mov_b32_e32 v137, v139
	v_mov_b32_e32 v136, v139
	v_mov_b32_e32 v135, v139
	v_mov_b32_e32 v134, v139
	v_mov_b32_e32 v133, v139
	v_mov_b32_e32 v132, v139
	v_mov_b32_e32 v131, v139
	v_mov_b32_e32 v130, v139
	v_mov_b32_e32 v129, v139
	v_mov_b32_e32 v128, v139
	v_mov_b32_e32 v127, v139
	v_mov_b32_e32 v126, v139
	v_mov_b32_e32 v125, v139
	v_mov_b32_e32 v124, v139
	v_mov_b32_e32 v115, v139
	v_mov_b32_e32 v114, v139
	v_mov_b32_e32 v113, v139
	v_mov_b32_e32 v112, v139
	v_mov_b32_e32 v111, v139
	v_mov_b32_e32 v110, v139
	v_mov_b32_e32 v109, v139
	v_mov_b32_e32 v108, v139
	v_mov_b32_e32 v107, v139
	v_mov_b32_e32 v106, v139
	v_mov_b32_e32 v105, v139
	v_mov_b32_e32 v104, v139
	v_mov_b32_e32 v103, v139
	v_mov_b32_e32 v102, v139
	v_mov_b32_e32 v101, v139
	v_mov_b32_e32 v100, v139
	v_mov_b32_e32 v67, v139
	v_mov_b32_e32 v66, v139
	v_mov_b32_e32 v65, v139
	v_mov_b32_e32 v64, v139
	v_mov_b32_e32 v59, v139
	v_mov_b32_e32 v58, v139
	v_mov_b32_e32 v57, v139
	v_mov_b32_e32 v56, v139
	v_mov_b32_e32 v63, v139
	v_mov_b32_e32 v62, v139
	v_mov_b32_e32 v61, v139
	v_mov_b32_e32 v60, v139
	v_mov_b32_e32 v55, v139
	v_mov_b32_e32 v54, v139
	v_mov_b32_e32 v53, v139
	v_mov_b32_e32 v52, v139
	v_mov_b32_e32 v51, v139
	v_mov_b32_e32 v50, v139
	v_mov_b32_e32 v49, v139
	v_mov_b32_e32 v48, v139
	v_mov_b32_e32 v43, v139
	v_mov_b32_e32 v42, v139
	v_mov_b32_e32 v41, v139
	v_mov_b32_e32 v40, v139
	v_mov_b32_e32 v47, v139
	v_mov_b32_e32 v46, v139
	v_mov_b32_e32 v45, v139
	v_mov_b32_e32 v44, v139
	v_mov_b32_e32 v39, v139
	v_mov_b32_e32 v38, v139
	v_mov_b32_e32 v37, v139
	v_mov_b32_e32 v36, v139
	v_mov_b32_e32 v99, v139
	v_mov_b32_e32 v98, v139
	v_mov_b32_e32 v97, v139
	v_mov_b32_e32 v96, v139
	v_mov_b32_e32 v95, v139
	v_mov_b32_e32 v94, v139
	v_mov_b32_e32 v93, v139
	v_mov_b32_e32 v92, v139
	v_mov_b32_e32 v91, v139
	v_mov_b32_e32 v90, v139
	v_mov_b32_e32 v89, v139
	v_mov_b32_e32 v88, v139
	v_mov_b32_e32 v87, v139
	v_mov_b32_e32 v86, v139
	v_mov_b32_e32 v85, v139
	v_mov_b32_e32 v84, v139
	v_mov_b32_e32 v83, v139
	v_mov_b32_e32 v82, v139
	v_mov_b32_e32 v81, v139
	v_mov_b32_e32 v80, v139
	v_mov_b32_e32 v79, v139
	v_mov_b32_e32 v78, v139
	v_mov_b32_e32 v77, v139
	v_mov_b32_e32 v76, v139
	v_mov_b32_e32 v75, v139
	v_mov_b32_e32 v74, v139
	v_mov_b32_e32 v73, v139
	v_mov_b32_e32 v72, v139
	v_mov_b32_e32 v71, v139
	v_mov_b32_e32 v70, v139
	v_mov_b32_e32 v69, v139
	v_mov_b32_e32 v68, v139
	v_mov_b32_e32 v35, v139
	v_mov_b32_e32 v34, v139
	v_mov_b32_e32 v33, v139
	v_mov_b32_e32 v32, v139
	v_mov_b32_e32 v31, v139
	v_mov_b32_e32 v30, v139
	v_mov_b32_e32 v29, v139
	v_mov_b32_e32 v28, v139
	v_mov_b32_e32 v27, v139
	v_mov_b32_e32 v26, v139
	v_mov_b32_e32 v25, v139
	v_mov_b32_e32 v24, v139
	v_mov_b32_e32 v15, v139
	v_mov_b32_e32 v14, v139
	v_mov_b32_e32 v13, v139
	v_mov_b32_e32 v12, v139
	v_mov_b32_e32 v23, v139
	v_mov_b32_e32 v22, v139
	v_mov_b32_e32 v21, v139
	v_mov_b32_e32 v20, v139
	v_mov_b32_e32 v11, v139
	v_mov_b32_e32 v10, v139
	v_mov_b32_e32 v9, v139
	v_mov_b32_e32 v8, v139
	v_mov_b32_e32 v19, v139
	v_mov_b32_e32 v18, v139
	v_mov_b32_e32 v17, v139
	v_mov_b32_e32 v16, v139
	v_mov_b32_e32 v7, v139
	v_mov_b32_e32 v6, v139
	v_mov_b32_e32 v5, v139
	v_mov_b32_e32 v4, v139
	s_cbranch_vccnz .LBB0_1072
	s_add_u32 s75, s38, 0x100
	s_addc_u32 s76, s39, 0
	s_add_u32 s4, s40, 0x80
	v_mov_b32_e32 v4, 0
	s_addc_u32 s5, s41, 0
	s_mov_b32 s40, 2
	v_mov_b32_e32 v5, v4
	v_mov_b32_e32 v6, v4
	v_mov_b32_e32 v7, v4
	v_mov_b32_e32 v16, v4
	v_mov_b32_e32 v17, v4
	v_mov_b32_e32 v18, v4
	v_mov_b32_e32 v19, v4
	v_mov_b32_e32 v8, v4
	v_mov_b32_e32 v9, v4
	v_mov_b32_e32 v10, v4
	v_mov_b32_e32 v11, v4
	v_mov_b32_e32 v20, v4
	v_mov_b32_e32 v21, v4
	v_mov_b32_e32 v22, v4
	v_mov_b32_e32 v23, v4
	v_mov_b32_e32 v12, v4
	v_mov_b32_e32 v13, v4
	v_mov_b32_e32 v14, v4
	v_mov_b32_e32 v15, v4
	v_mov_b32_e32 v24, v4
	v_mov_b32_e32 v25, v4
	v_mov_b32_e32 v26, v4
	v_mov_b32_e32 v27, v4
	v_mov_b32_e32 v28, v4
	v_mov_b32_e32 v29, v4
	v_mov_b32_e32 v30, v4
	v_mov_b32_e32 v31, v4
	v_mov_b32_e32 v32, v4
	v_mov_b32_e32 v33, v4
	v_mov_b32_e32 v34, v4
	v_mov_b32_e32 v35, v4
	v_mov_b32_e32 v68, v4
	v_mov_b32_e32 v69, v4
	v_mov_b32_e32 v70, v4
	v_mov_b32_e32 v71, v4
	v_mov_b32_e32 v72, v4
	v_mov_b32_e32 v73, v4
	v_mov_b32_e32 v74, v4
	v_mov_b32_e32 v75, v4
	v_mov_b32_e32 v76, v4
	v_mov_b32_e32 v77, v4
	v_mov_b32_e32 v78, v4
	v_mov_b32_e32 v79, v4
	v_mov_b32_e32 v80, v4
	v_mov_b32_e32 v81, v4
	v_mov_b32_e32 v82, v4
	v_mov_b32_e32 v83, v4
	v_mov_b32_e32 v84, v4
	v_mov_b32_e32 v85, v4
	v_mov_b32_e32 v86, v4
	v_mov_b32_e32 v87, v4
	v_mov_b32_e32 v88, v4
	v_mov_b32_e32 v89, v4
	v_mov_b32_e32 v90, v4
	v_mov_b32_e32 v91, v4
	v_mov_b32_e32 v92, v4
	v_mov_b32_e32 v93, v4
	v_mov_b32_e32 v94, v4
	v_mov_b32_e32 v95, v4
	v_mov_b32_e32 v96, v4
	v_mov_b32_e32 v97, v4
	v_mov_b32_e32 v98, v4
	v_mov_b32_e32 v99, v4
	v_mov_b32_e32 v36, v4
	v_mov_b32_e32 v37, v4
	v_mov_b32_e32 v38, v4
	v_mov_b32_e32 v39, v4
	v_mov_b32_e32 v44, v4
	v_mov_b32_e32 v45, v4
	v_mov_b32_e32 v46, v4
	v_mov_b32_e32 v47, v4
	v_mov_b32_e32 v40, v4
	v_mov_b32_e32 v41, v4
	v_mov_b32_e32 v42, v4
	v_mov_b32_e32 v43, v4
	v_mov_b32_e32 v48, v4
	v_mov_b32_e32 v49, v4
	v_mov_b32_e32 v50, v4
	v_mov_b32_e32 v51, v4
	v_mov_b32_e32 v52, v4
	v_mov_b32_e32 v53, v4
	v_mov_b32_e32 v54, v4
	v_mov_b32_e32 v55, v4
	v_mov_b32_e32 v60, v4
	v_mov_b32_e32 v61, v4
	v_mov_b32_e32 v62, v4
	v_mov_b32_e32 v63, v4
	v_mov_b32_e32 v56, v4
	v_mov_b32_e32 v57, v4
	v_mov_b32_e32 v58, v4
	v_mov_b32_e32 v59, v4
	v_mov_b32_e32 v64, v4
	v_mov_b32_e32 v65, v4
	v_mov_b32_e32 v66, v4
	v_mov_b32_e32 v67, v4
	v_mov_b32_e32 v100, v4
	v_mov_b32_e32 v101, v4
	v_mov_b32_e32 v102, v4
	v_mov_b32_e32 v103, v4
	v_mov_b32_e32 v104, v4
	v_mov_b32_e32 v105, v4
	v_mov_b32_e32 v106, v4
	v_mov_b32_e32 v107, v4
	v_mov_b32_e32 v108, v4
	v_mov_b32_e32 v109, v4
	v_mov_b32_e32 v110, v4
	v_mov_b32_e32 v111, v4
	v_mov_b32_e32 v112, v4
	v_mov_b32_e32 v113, v4
	v_mov_b32_e32 v114, v4
	v_mov_b32_e32 v115, v4
	v_mov_b32_e32 v124, v4
	v_mov_b32_e32 v125, v4
	v_mov_b32_e32 v126, v4
	v_mov_b32_e32 v127, v4
	v_mov_b32_e32 v128, v4
	v_mov_b32_e32 v129, v4
	v_mov_b32_e32 v130, v4
	v_mov_b32_e32 v131, v4
	v_mov_b32_e32 v132, v4
	v_mov_b32_e32 v133, v4
	v_mov_b32_e32 v134, v4
	v_mov_b32_e32 v135, v4
	v_mov_b32_e32 v136, v4
	v_mov_b32_e32 v137, v4
	v_mov_b32_e32 v138, v4
	v_mov_b32_e32 v139, v4
	.p2align	6

; template <class Epi, class Sched, bool ALIGN_EPI = false, bool SP2 = false>
; __device__ __forceinline__ void gemm_phase(PG8_LAS unsigned char* lds, const Gemm g, const Sched& S, const Epi& E, int tid_in) {
;     ...
;         for (int t = 0; t < nt; t += 2) {
;             const bool last = (t == nt - 2);
;             if constexpr (mid_hook<Epi>::value) { if (t == Epi::H1 || t == Epi::H2) E.mid(acc, cur, wr, wc, fr, fq, t == Epi::H2); }
;             const char* a1 = cA + (size_t)(t + 1) * kstep + (t >= jt ? jb : 0);
;             const char* a2 = last ? nA : cA + (size_t)(t + 2) * kstep + (t + 2 >= jt ? jb : 0); const char* b2 = last ? nB : cB + (size_t)(t + 2) * kstep;
;             const char* a3 = a2 + kstep; const char* b3 = b2 + kstep;
;     ...
; #pragma unroll
;         for (int a = 0; a < 2; ++a)
; #pragma unroll
;             for (int b = 0; b < 2; ++b)
; #pragma unroll
;                 for (int m = 0; m < 4; ++m)
; #pragma unroll
;                     for (int n = 0; n < 2; ++n) acc[a][b][m][n] = (f32x4){0.f, 0.f, 0.f, 0.f};
;         cur = nxt; cA = nA; cB = nB; ++ui;
.LBB0_1100:
	v_mov_b32_e32 v127, 0
	s_andn2_b64 vcc, exec, s[0:1]
	v_mov_b32_e32 v126, v127
	v_mov_b32_e32 v125, v127
	v_mov_b32_e32 v124, v127
	v_mov_b32_e32 v131, v127
	v_mov_b32_e32 v130, v127
	v_mov_b32_e32 v129, v127
	v_mov_b32_e32 v128, v127
	v_mov_b32_e32 v115, v127
	v_mov_b32_e32 v114, v127
	v_mov_b32_e32 v113, v127
	v_mov_b32_e32 v112, v127
	v_mov_b32_e32 v111, v127
	v_mov_b32_e32 v110, v127
	v_mov_b32_e32 v109, v127
	v_mov_b32_e32 v108, v127
	v_mov_b32_e32 v99, v127
	v_mov_b32_e32 v98, v127
	v_mov_b32_e32 v97, v127
	v_mov_b32_e32 v96, v127
	v_mov_b32_e32 v95, v127
	v_mov_b32_e32 v94, v127
	v_mov_b32_e32 v93, v127
	v_mov_b32_e32 v92, v127
	v_mov_b32_e32 v83, v127
	v_mov_b32_e32 v82, v127
	v_mov_b32_e32 v81, v127
	v_mov_b32_e32 v80, v127
	v_mov_b32_e32 v79, v127
	v_mov_b32_e32 v78, v127
	v_mov_b32_e32 v77, v127
	v_mov_b32_e32 v76, v127
	v_mov_b32_e32 v123, v127
	v_mov_b32_e32 v122, v127
	v_mov_b32_e32 v121, v127
	v_mov_b32_e32 v120, v127
	v_mov_b32_e32 v119, v127
	v_mov_b32_e32 v118, v127
	v_mov_b32_e32 v117, v127
	v_mov_b32_e32 v116, v127
	v_mov_b32_e32 v107, v127
	v_mov_b32_e32 v106, v127
	v_mov_b32_e32 v105, v127
	v_mov_b32_e32 v104, v127
	v_mov_b32_e32 v103, v127
	v_mov_b32_e32 v102, v127
	v_mov_b32_e32 v101, v127
	v_mov_b32_e32 v100, v127
	v_mov_b32_e32 v91, v127
	v_mov_b32_e32 v90, v127
	v_mov_b32_e32 v89, v127
	v_mov_b32_e32 v88, v127
	v_mov_b32_e32 v87, v127
	v_mov_b32_e32 v86, v127
	v_mov_b32_e32 v85, v127
	v_mov_b32_e32 v84, v127
	v_mov_b32_e32 v75, v127
	v_mov_b32_e32 v74, v127
	v_mov_b32_e32 v73, v127
	v_mov_b32_e32 v72, v127
	v_mov_b32_e32 v71, v127
	v_mov_b32_e32 v70, v127
	v_mov_b32_e32 v69, v127
	v_mov_b32_e32 v68, v127
	v_mov_b32_e32 v67, v127
	v_mov_b32_e32 v66, v127
	v_mov_b32_e32 v65, v127
	v_mov_b32_e32 v64, v127
	v_mov_b32_e32 v63, v127
	v_mov_b32_e32 v62, v127
	v_mov_b32_e32 v61, v127
	v_mov_b32_e32 v60, v127
	v_mov_b32_e32 v51, v127
	v_mov_b32_e32 v50, v127
	v_mov_b32_e32 v49, v127
	v_mov_b32_e32 v48, v127
	v_mov_b32_e32 v47, v127
	v_mov_b32_e32 v46, v127
	v_mov_b32_e32 v45, v127
	v_mov_b32_e32 v44, v127
	v_mov_b32_e32 v35, v127
	v_mov_b32_e32 v34, v127
	v_mov_b32_e32 v33, v127
	v_mov_b32_e32 v32, v127
	v_mov_b32_e32 v31, v127
	v_mov_b32_e32 v30, v127
	v_mov_b32_e32 v29, v127
	v_mov_b32_e32 v28, v127
	v_mov_b32_e32 v19, v127
	v_mov_b32_e32 v18, v127
	v_mov_b32_e32 v17, v127
	v_mov_b32_e32 v16, v127
	v_mov_b32_e32 v15, v127
	v_mov_b32_e32 v14, v127
	v_mov_b32_e32 v13, v127
	v_mov_b32_e32 v12, v127
	v_mov_b32_e32 v59, v127
	v_mov_b32_e32 v58, v127
	v_mov_b32_e32 v57, v127
	v_mov_b32_e32 v56, v127
	v_mov_b32_e32 v55, v127
	v_mov_b32_e32 v54, v127
	v_mov_b32_e32 v53, v127
	v_mov_b32_e32 v52, v127
	v_mov_b32_e32 v43, v127
	v_mov_b32_e32 v42, v127
	v_mov_b32_e32 v41, v127
	v_mov_b32_e32 v40, v127
	v_mov_b32_e32 v39, v127
	v_mov_b32_e32 v38, v127
	v_mov_b32_e32 v37, v127
	v_mov_b32_e32 v36, v127
	v_mov_b32_e32 v27, v127
	v_mov_b32_e32 v26, v127
	v_mov_b32_e32 v25, v127
	v_mov_b32_e32 v24, v127
	v_mov_b32_e32 v23, v127
	v_mov_b32_e32 v22, v127
	v_mov_b32_e32 v21, v127
	v_mov_b32_e32 v20, v127
	v_mov_b32_e32 v11, v127
	v_mov_b32_e32 v10, v127
	v_mov_b32_e32 v9, v127
	v_mov_b32_e32 v8, v127
	v_mov_b32_e32 v7, v127
	v_mov_b32_e32 v6, v127
	v_mov_b32_e32 v5, v127
	v_mov_b32_e32 v4, v127
	s_cbranch_vccnz .LBB0_1103
	s_add_u32 s17, s24, 0x100
	s_addc_u32 s21, s25, 0
	s_add_u32 s24, s26, 0x80
	v_mov_b32_e32 v4, 0
	s_addc_u32 s25, s27, 0
	s_mov_b32 s55, 2
	v_mov_b32_e32 v5, v4
	v_mov_b32_e32 v6, v4
	v_mov_b32_e32 v7, v4
	v_mov_b32_e32 v8, v4
	v_mov_b32_e32 v9, v4
	v_mov_b32_e32 v10, v4
	v_mov_b32_e32 v11, v4
	v_mov_b32_e32 v20, v4
	v_mov_b32_e32 v21, v4
	v_mov_b32_e32 v22, v4
	v_mov_b32_e32 v23, v4
	v_mov_b32_e32 v24, v4
	v_mov_b32_e32 v25, v4
	v_mov_b32_e32 v26, v4
	v_mov_b32_e32 v27, v4
	v_mov_b32_e32 v36, v4
	v_mov_b32_e32 v37, v4
	v_mov_b32_e32 v38, v4
	v_mov_b32_e32 v39, v4
	v_mov_b32_e32 v40, v4
	v_mov_b32_e32 v41, v4
	v_mov_b32_e32 v42, v4
	v_mov_b32_e32 v43, v4
	v_mov_b32_e32 v52, v4
	v_mov_b32_e32 v53, v4
	v_mov_b32_e32 v54, v4
	v_mov_b32_e32 v55, v4
	v_mov_b32_e32 v56, v4
	v_mov_b32_e32 v57, v4
	v_mov_b32_e32 v58, v4
	v_mov_b32_e32 v59, v4
	v_mov_b32_e32 v12, v4
	v_mov_b32_e32 v13, v4
	v_mov_b32_e32 v14, v4
	v_mov_b32_e32 v15, v4
	v_mov_b32_e32 v16, v4
	v_mov_b32_e32 v17, v4
	v_mov_b32_e32 v18, v4
	v_mov_b32_e32 v19, v4
	v_mov_b32_e32 v28, v4
	v_mov_b32_e32 v29, v4
	v_mov_b32_e32 v30, v4
	v_mov_b32_e32 v31, v4
	v_mov_b32_e32 v32, v4
	v_mov_b32_e32 v33, v4
	v_mov_b32_e32 v34, v4
	v_mov_b32_e32 v35, v4
	v_mov_b32_e32 v44, v4
	v_mov_b32_e32 v45, v4
	v_mov_b32_e32 v46, v4
	v_mov_b32_e32 v47, v4
	v_mov_b32_e32 v48, v4
	v_mov_b32_e32 v49, v4
	v_mov_b32_e32 v50, v4
	v_mov_b32_e32 v51, v4
	v_mov_b32_e32 v60, v4
	v_mov_b32_e32 v61, v4
	v_mov_b32_e32 v62, v4
	v_mov_b32_e32 v63, v4
	v_mov_b32_e32 v64, v4
	v_mov_b32_e32 v65, v4
	v_mov_b32_e32 v66, v4
	v_mov_b32_e32 v67, v4
	v_mov_b32_e32 v68, v4
	v_mov_b32_e32 v69, v4
	v_mov_b32_e32 v70, v4
	v_mov_b32_e32 v71, v4
	v_mov_b32_e32 v72, v4
	v_mov_b32_e32 v73, v4
	v_mov_b32_e32 v74, v4
	v_mov_b32_e32 v75, v4
	v_mov_b32_e32 v84, v4
	v_mov_b32_e32 v85, v4
	v_mov_b32_e32 v86, v4
	v_mov_b32_e32 v87, v4
	v_mov_b32_e32 v88, v4
	v_mov_b32_e32 v89, v4
	v_mov_b32_e32 v90, v4
	v_mov_b32_e32 v91, v4
	v_mov_b32_e32 v100, v4
	v_mov_b32_e32 v101, v4
	v_mov_b32_e32 v102, v4
	v_mov_b32_e32 v103, v4
	v_mov_b32_e32 v104, v4
	v_mov_b32_e32 v105, v4
	v_mov_b32_e32 v106, v4
	v_mov_b32_e32 v107, v4
	v_mov_b32_e32 v116, v4
	v_mov_b32_e32 v117, v4
	v_mov_b32_e32 v118, v4
	v_mov_b32_e32 v119, v4
	v_mov_b32_e32 v120, v4
	v_mov_b32_e32 v121, v4
	v_mov_b32_e32 v122, v4
	v_mov_b32_e32 v123, v4
	v_mov_b32_e32 v76, v4
	v_mov_b32_e32 v77, v4
	v_mov_b32_e32 v78, v4
	v_mov_b32_e32 v79, v4
	v_mov_b32_e32 v80, v4
	v_mov_b32_e32 v81, v4
	v_mov_b32_e32 v82, v4
	v_mov_b32_e32 v83, v4
	v_mov_b32_e32 v92, v4
	v_mov_b32_e32 v93, v4
	v_mov_b32_e32 v94, v4
	v_mov_b32_e32 v95, v4
	v_mov_b32_e32 v96, v4
	v_mov_b32_e32 v97, v4
	v_mov_b32_e32 v98, v4
	v_mov_b32_e32 v99, v4
	v_mov_b32_e32 v108, v4
	v_mov_b32_e32 v109, v4
	v_mov_b32_e32 v110, v4
	v_mov_b32_e32 v111, v4
	v_mov_b32_e32 v112, v4
	v_mov_b32_e32 v113, v4
	v_mov_b32_e32 v114, v4
	v_mov_b32_e32 v115, v4
	v_mov_b32_e32 v128, v4
	v_mov_b32_e32 v129, v4
	v_mov_b32_e32 v130, v4
	v_mov_b32_e32 v131, v4
	v_mov_b32_e32 v124, v4
	v_mov_b32_e32 v125, v4
	v_mov_b32_e32 v126, v4
	v_mov_b32_e32 v127, v4
	.p2align	6

; template <class Epi, class Sched, bool ALIGN_EPI = false, bool SP2 = false>
; __device__ __forceinline__ void gemm_phase(PG8_LAS unsigned char* lds, const Gemm g, const Sched& S, const Epi& E, int tid_in) {
;     ...
;         for (int t = 0; t < nt; t += 2) {
;             const bool last = (t == nt - 2);
;             if constexpr (mid_hook<Epi>::value) { if (t == Epi::H1 || t == Epi::H2) E.mid(acc, cur, wr, wc, fr, fq, t == Epi::H2); }
;             const char* a1 = cA + (size_t)(t + 1) * kstep + (t >= jt ? jb : 0);
;             const char* a2 = last ? nA : cA + (size_t)(t + 2) * kstep + (t + 2 >= jt ? jb : 0); const char* b2 = last ? nB : cB + (size_t)(t + 2) * kstep;
;             const char* a3 = a2 + kstep; const char* b3 = b2 + kstep;
;     ...
; #pragma unroll
;         for (int a = 0; a < 2; ++a)
; #pragma unroll
;             for (int b = 0; b < 2; ++b)
; #pragma unroll
;                 for (int m = 0; m < 4; ++m)
; #pragma unroll
;                     for (int n = 0; n < 2; ++n) acc[a][b][m][n] = (f32x4){0.f, 0.f, 0.f, 0.f};
;         cur = nxt; cA = nA; cB = nB; ++ui;
.LBB0_1253:
	v_mov_b32_e32 v127, 0
	s_andn2_b64 vcc, exec, s[16:17]
	v_mov_b32_e32 v126, v127
	v_mov_b32_e32 v125, v127
	v_mov_b32_e32 v124, v127
	v_mov_b32_e32 v123, v127
	v_mov_b32_e32 v122, v127
	v_mov_b32_e32 v121, v127
	v_mov_b32_e32 v120, v127
	v_mov_b32_e32 v115, v127
	v_mov_b32_e32 v114, v127
	v_mov_b32_e32 v113, v127
	v_mov_b32_e32 v112, v127
	v_mov_b32_e32 v107, v127
	v_mov_b32_e32 v106, v127
	v_mov_b32_e32 v105, v127
	v_mov_b32_e32 v104, v127
	v_mov_b32_e32 v99, v127
	v_mov_b32_e32 v98, v127
	v_mov_b32_e32 v97, v127
	v_mov_b32_e32 v96, v127
	v_mov_b32_e32 v91, v127
	v_mov_b32_e32 v90, v127
	v_mov_b32_e32 v89, v127
	v_mov_b32_e32 v88, v127
	v_mov_b32_e32 v83, v127
	v_mov_b32_e32 v82, v127
	v_mov_b32_e32 v81, v127
	v_mov_b32_e32 v80, v127
	v_mov_b32_e32 v75, v127
	v_mov_b32_e32 v74, v127
	v_mov_b32_e32 v73, v127
	v_mov_b32_e32 v72, v127
	v_mov_b32_e32 v131, v127
	v_mov_b32_e32 v130, v127
	v_mov_b32_e32 v129, v127
	v_mov_b32_e32 v128, v127
	v_mov_b32_e32 v119, v127
	v_mov_b32_e32 v118, v127
	v_mov_b32_e32 v117, v127
	v_mov_b32_e32 v116, v127
	v_mov_b32_e32 v111, v127
	v_mov_b32_e32 v110, v127
	v_mov_b32_e32 v109, v127
	v_mov_b32_e32 v108, v127
	v_mov_b32_e32 v103, v127
	v_mov_b32_e32 v102, v127
	v_mov_b32_e32 v101, v127
	v_mov_b32_e32 v100, v127
	v_mov_b32_e32 v95, v127
	v_mov_b32_e32 v94, v127
	v_mov_b32_e32 v93, v127
	v_mov_b32_e32 v92, v127
	v_mov_b32_e32 v87, v127
	v_mov_b32_e32 v86, v127
	v_mov_b32_e32 v85, v127
	v_mov_b32_e32 v84, v127
	v_mov_b32_e32 v79, v127
	v_mov_b32_e32 v78, v127
	v_mov_b32_e32 v77, v127
	v_mov_b32_e32 v76, v127
	v_mov_b32_e32 v71, v127
	v_mov_b32_e32 v70, v127
	v_mov_b32_e32 v69, v127
	v_mov_b32_e32 v68, v127
	v_mov_b32_e32 v67, v127
	v_mov_b32_e32 v66, v127
	v_mov_b32_e32 v65, v127
	v_mov_b32_e32 v64, v127
	v_mov_b32_e32 v59, v127
	v_mov_b32_e32 v58, v127
	v_mov_b32_e32 v57, v127
	v_mov_b32_e32 v56, v127
	v_mov_b32_e32 v51, v127
	v_mov_b32_e32 v50, v127
	v_mov_b32_e32 v49, v127
	v_mov_b32_e32 v48, v127
	v_mov_b32_e32 v43, v127
	v_mov_b32_e32 v42, v127
	v_mov_b32_e32 v41, v127
	v_mov_b32_e32 v40, v127
	v_mov_b32_e32 v35, v127
	v_mov_b32_e32 v34, v127
	v_mov_b32_e32 v33, v127
	v_mov_b32_e32 v32, v127
	v_mov_b32_e32 v27, v127
	v_mov_b32_e32 v26, v127
	v_mov_b32_e32 v25, v127
	v_mov_b32_e32 v24, v127
	v_mov_b32_e32 v19, v127
	v_mov_b32_e32 v18, v127
	v_mov_b32_e32 v17, v127
	v_mov_b32_e32 v16, v127
	v_mov_b32_e32 v11, v127
	v_mov_b32_e32 v10, v127
	v_mov_b32_e32 v9, v127
	v_mov_b32_e32 v8, v127
	v_mov_b32_e32 v63, v127
	v_mov_b32_e32 v62, v127
	v_mov_b32_e32 v61, v127
	v_mov_b32_e32 v60, v127
	v_mov_b32_e32 v55, v127
	v_mov_b32_e32 v54, v127
	v_mov_b32_e32 v53, v127
	v_mov_b32_e32 v52, v127
	v_mov_b32_e32 v47, v127
	v_mov_b32_e32 v46, v127
	v_mov_b32_e32 v45, v127
	v_mov_b32_e32 v44, v127
	v_mov_b32_e32 v39, v127
	v_mov_b32_e32 v38, v127
	v_mov_b32_e32 v37, v127
	v_mov_b32_e32 v36, v127
	v_mov_b32_e32 v31, v127
	v_mov_b32_e32 v30, v127
	v_mov_b32_e32 v29, v127
	v_mov_b32_e32 v28, v127
	v_mov_b32_e32 v23, v127
	v_mov_b32_e32 v22, v127
	v_mov_b32_e32 v21, v127
	v_mov_b32_e32 v20, v127
	v_mov_b32_e32 v15, v127
	v_mov_b32_e32 v14, v127
	v_mov_b32_e32 v13, v127
	v_mov_b32_e32 v12, v127
	v_mov_b32_e32 v7, v127
	v_mov_b32_e32 v6, v127
	v_mov_b32_e32 v5, v127
	v_mov_b32_e32 v4, v127
	s_cbranch_vccnz .LBB0_1256
	s_add_u32 s54, s22, 0x100
	s_addc_u32 s55, s23, 0
	s_add_u32 s22, s24, 0x80
	v_mov_b32_e32 v4, 0
	s_addc_u32 s23, s25, 0
	s_mov_b32 s58, 2
	v_mov_b32_e32 v5, v4
	v_mov_b32_e32 v6, v4
	v_mov_b32_e32 v7, v4
	v_mov_b32_e32 v12, v4
	v_mov_b32_e32 v13, v4
	v_mov_b32_e32 v14, v4
	v_mov_b32_e32 v15, v4
	v_mov_b32_e32 v20, v4
	v_mov_b32_e32 v21, v4
	v_mov_b32_e32 v22, v4
	v_mov_b32_e32 v23, v4
	v_mov_b32_e32 v28, v4
	v_mov_b32_e32 v29, v4
	v_mov_b32_e32 v30, v4
	v_mov_b32_e32 v31, v4
	v_mov_b32_e32 v36, v4
	v_mov_b32_e32 v37, v4
	v_mov_b32_e32 v38, v4
	v_mov_b32_e32 v39, v4
	v_mov_b32_e32 v44, v4
	v_mov_b32_e32 v45, v4
	v_mov_b32_e32 v46, v4
	v_mov_b32_e32 v47, v4
	v_mov_b32_e32 v52, v4
	v_mov_b32_e32 v53, v4
	v_mov_b32_e32 v54, v4
	v_mov_b32_e32 v55, v4
	v_mov_b32_e32 v60, v4
	v_mov_b32_e32 v61, v4
	v_mov_b32_e32 v62, v4
	v_mov_b32_e32 v63, v4
	v_mov_b32_e32 v8, v4
	v_mov_b32_e32 v9, v4
	v_mov_b32_e32 v10, v4
	v_mov_b32_e32 v11, v4
	v_mov_b32_e32 v16, v4
	v_mov_b32_e32 v17, v4
	v_mov_b32_e32 v18, v4
	v_mov_b32_e32 v19, v4
	v_mov_b32_e32 v24, v4
	v_mov_b32_e32 v25, v4
	v_mov_b32_e32 v26, v4
	v_mov_b32_e32 v27, v4
	v_mov_b32_e32 v32, v4
	v_mov_b32_e32 v33, v4
	v_mov_b32_e32 v34, v4
	v_mov_b32_e32 v35, v4
	v_mov_b32_e32 v40, v4
	v_mov_b32_e32 v41, v4
	v_mov_b32_e32 v42, v4
	v_mov_b32_e32 v43, v4
	v_mov_b32_e32 v48, v4
	v_mov_b32_e32 v49, v4
	v_mov_b32_e32 v50, v4
	v_mov_b32_e32 v51, v4
	v_mov_b32_e32 v56, v4
	v_mov_b32_e32 v57, v4
	v_mov_b32_e32 v58, v4
	v_mov_b32_e32 v59, v4
	v_mov_b32_e32 v64, v4
	v_mov_b32_e32 v65, v4
	v_mov_b32_e32 v66, v4
	v_mov_b32_e32 v67, v4
	v_mov_b32_e32 v68, v4
	v_mov_b32_e32 v69, v4
	v_mov_b32_e32 v70, v4
	v_mov_b32_e32 v71, v4
	v_mov_b32_e32 v76, v4
	v_mov_b32_e32 v77, v4
	v_mov_b32_e32 v78, v4
	v_mov_b32_e32 v79, v4
	v_mov_b32_e32 v84, v4
	v_mov_b32_e32 v85, v4
	v_mov_b32_e32 v86, v4
	v_mov_b32_e32 v87, v4
	v_mov_b32_e32 v92, v4
	v_mov_b32_e32 v93, v4
	v_mov_b32_e32 v94, v4
	v_mov_b32_e32 v95, v4
	v_mov_b32_e32 v100, v4
	v_mov_b32_e32 v101, v4
	v_mov_b32_e32 v102, v4
	v_mov_b32_e32 v103, v4
	v_mov_b32_e32 v108, v4
	v_mov_b32_e32 v109, v4
	v_mov_b32_e32 v110, v4
	v_mov_b32_e32 v111, v4
	v_mov_b32_e32 v116, v4
	v_mov_b32_e32 v117, v4
	v_mov_b32_e32 v118, v4
	v_mov_b32_e32 v119, v4
	v_mov_b32_e32 v128, v4
	v_mov_b32_e32 v129, v4
	v_mov_b32_e32 v130, v4
	v_mov_b32_e32 v131, v4
	v_mov_b32_e32 v72, v4
	v_mov_b32_e32 v73, v4
	v_mov_b32_e32 v74, v4
	v_mov_b32_e32 v75, v4
	v_mov_b32_e32 v80, v4
	v_mov_b32_e32 v81, v4
	v_mov_b32_e32 v82, v4
	v_mov_b32_e32 v83, v4
	v_mov_b32_e32 v88, v4
	v_mov_b32_e32 v89, v4
	v_mov_b32_e32 v90, v4
	v_mov_b32_e32 v91, v4
	v_mov_b32_e32 v96, v4
	v_mov_b32_e32 v97, v4
	v_mov_b32_e32 v98, v4
	v_mov_b32_e32 v99, v4
	v_mov_b32_e32 v104, v4
	v_mov_b32_e32 v105, v4
	v_mov_b32_e32 v106, v4
	v_mov_b32_e32 v107, v4
	v_mov_b32_e32 v112, v4
	v_mov_b32_e32 v113, v4
	v_mov_b32_e32 v114, v4
	v_mov_b32_e32 v115, v4
	v_mov_b32_e32 v120, v4
	v_mov_b32_e32 v121, v4
	v_mov_b32_e32 v122, v4
	v_mov_b32_e32 v123, v4
	v_mov_b32_e32 v124, v4
	v_mov_b32_e32 v125, v4
	v_mov_b32_e32 v126, v4
	v_mov_b32_e32 v127, v4
	.p2align	6

; template <class Epi, class Sched, bool ALIGN_EPI = false, bool SP2 = false>
; __device__ __forceinline__ void gemm_phase(PG8_LAS unsigned char* lds, const Gemm g, const Sched& S, const Epi& E, int tid_in) {
;     ...
;         for (int t = 0; t < nt; t += 2) {
;             const bool last = (t == nt - 2);
;             if constexpr (mid_hook<Epi>::value) { if (t == Epi::H1 || t == Epi::H2) E.mid(acc, cur, wr, wc, fr, fq, t == Epi::H2); }
;             const char* a1 = cA + (size_t)(t + 1) * kstep + (t >= jt ? jb : 0);
;             const char* a2 = last ? nA : cA + (size_t)(t + 2) * kstep + (t + 2 >= jt ? jb : 0); const char* b2 = last ? nB : cB + (size_t)(t + 2) * kstep;
;             const char* a3 = a2 + kstep; const char* b3 = b2 + kstep;
;     ...
; #pragma unroll
;         for (int a = 0; a < 2; ++a)
; #pragma unroll
;             for (int b = 0; b < 2; ++b)
; #pragma unroll
;                 for (int m = 0; m < 4; ++m)
; #pragma unroll
;                     for (int n = 0; n < 2; ++n) acc[a][b][m][n] = (f32x4){0.f, 0.f, 0.f, 0.f};
;         cur = nxt; cA = nA; cB = nB; ++ui;
.LBB0_1329:
	v_mov_b32_e32 v131, 0
	s_andn2_b64 vcc, exec, s[22:23]
	v_mov_b32_e32 v130, v131
	v_mov_b32_e32 v129, v131
	v_mov_b32_e32 v128, v131
	v_mov_b32_e32 v127, v131
	v_mov_b32_e32 v126, v131
	v_mov_b32_e32 v125, v131
	v_mov_b32_e32 v124, v131
	v_mov_b32_e32 v123, v131
	v_mov_b32_e32 v122, v131
	v_mov_b32_e32 v121, v131
	v_mov_b32_e32 v120, v131
	v_mov_b32_e32 v119, v131
	v_mov_b32_e32 v118, v131
	v_mov_b32_e32 v117, v131
	v_mov_b32_e32 v116, v131
	v_mov_b32_e32 v115, v131
	v_mov_b32_e32 v114, v131
	v_mov_b32_e32 v113, v131
	v_mov_b32_e32 v112, v131
	v_mov_b32_e32 v111, v131
	v_mov_b32_e32 v110, v131
	v_mov_b32_e32 v109, v131
	v_mov_b32_e32 v108, v131
	v_mov_b32_e32 v107, v131
	v_mov_b32_e32 v106, v131
	v_mov_b32_e32 v105, v131
	v_mov_b32_e32 v104, v131
	v_mov_b32_e32 v103, v131
	v_mov_b32_e32 v102, v131
	v_mov_b32_e32 v101, v131
	v_mov_b32_e32 v100, v131
	v_mov_b32_e32 v67, v131
	v_mov_b32_e32 v66, v131
	v_mov_b32_e32 v65, v131
	v_mov_b32_e32 v64, v131
	v_mov_b32_e32 v59, v131
	v_mov_b32_e32 v58, v131
	v_mov_b32_e32 v57, v131
	v_mov_b32_e32 v56, v131
	v_mov_b32_e32 v63, v131
	v_mov_b32_e32 v62, v131
	v_mov_b32_e32 v61, v131
	v_mov_b32_e32 v60, v131
	v_mov_b32_e32 v55, v131
	v_mov_b32_e32 v54, v131
	v_mov_b32_e32 v53, v131
	v_mov_b32_e32 v52, v131
	v_mov_b32_e32 v51, v131
	v_mov_b32_e32 v50, v131
	v_mov_b32_e32 v49, v131
	v_mov_b32_e32 v48, v131
	v_mov_b32_e32 v43, v131
	v_mov_b32_e32 v42, v131
	v_mov_b32_e32 v41, v131
	v_mov_b32_e32 v40, v131
	v_mov_b32_e32 v47, v131
	v_mov_b32_e32 v46, v131
	v_mov_b32_e32 v45, v131
	v_mov_b32_e32 v44, v131
	v_mov_b32_e32 v39, v131
	v_mov_b32_e32 v38, v131
	v_mov_b32_e32 v37, v131
	v_mov_b32_e32 v36, v131
	v_mov_b32_e32 v99, v131
	v_mov_b32_e32 v98, v131
	v_mov_b32_e32 v97, v131
	v_mov_b32_e32 v96, v131
	v_mov_b32_e32 v95, v131
	v_mov_b32_e32 v94, v131
	v_mov_b32_e32 v93, v131
	v_mov_b32_e32 v92, v131
	v_mov_b32_e32 v91, v131
	v_mov_b32_e32 v90, v131
	v_mov_b32_e32 v89, v131
	v_mov_b32_e32 v88, v131
	v_mov_b32_e32 v87, v131
	v_mov_b32_e32 v86, v131
	v_mov_b32_e32 v85, v131
	v_mov_b32_e32 v84, v131
	v_mov_b32_e32 v83, v131
	v_mov_b32_e32 v82, v131
	v_mov_b32_e32 v81, v131
	v_mov_b32_e32 v80, v131
	v_mov_b32_e32 v79, v131
	v_mov_b32_e32 v78, v131
	v_mov_b32_e32 v77, v131
	v_mov_b32_e32 v76, v131
	v_mov_b32_e32 v75, v131
	v_mov_b32_e32 v74, v131
	v_mov_b32_e32 v73, v131
	v_mov_b32_e32 v72, v131
	v_mov_b32_e32 v71, v131
	v_mov_b32_e32 v70, v131
	v_mov_b32_e32 v69, v131
	v_mov_b32_e32 v68, v131
	v_mov_b32_e32 v35, v131
	v_mov_b32_e32 v34, v131
	v_mov_b32_e32 v33, v131
	v_mov_b32_e32 v32, v131
	v_mov_b32_e32 v31, v131
	v_mov_b32_e32 v30, v131
	v_mov_b32_e32 v29, v131
	v_mov_b32_e32 v28, v131
	v_mov_b32_e32 v27, v131
	v_mov_b32_e32 v26, v131
	v_mov_b32_e32 v25, v131
	v_mov_b32_e32 v24, v131
	v_mov_b32_e32 v15, v131
	v_mov_b32_e32 v14, v131
	v_mov_b32_e32 v13, v131
	v_mov_b32_e32 v12, v131
	v_mov_b32_e32 v23, v131
	v_mov_b32_e32 v22, v131
	v_mov_b32_e32 v21, v131
	v_mov_b32_e32 v20, v131
	v_mov_b32_e32 v11, v131
	v_mov_b32_e32 v10, v131
	v_mov_b32_e32 v9, v131
	v_mov_b32_e32 v8, v131
	v_mov_b32_e32 v19, v131
	v_mov_b32_e32 v18, v131
	v_mov_b32_e32 v17, v131
	v_mov_b32_e32 v16, v131
	v_mov_b32_e32 v7, v131
	v_mov_b32_e32 v6, v131
	v_mov_b32_e32 v5, v131
	v_mov_b32_e32 v4, v131
	s_cbranch_vccnz .LBB0_1333
	s_add_u32 s74, s38, 0x100
	s_addc_u32 s75, s39, 0
	s_add_u32 s4, s40, 0x80
	v_mov_b32_e32 v4, 0
	s_addc_u32 s5, s41, 0
	s_mov_b32 s40, 2
	v_mov_b32_e32 v5, v4
	v_mov_b32_e32 v6, v4
	v_mov_b32_e32 v7, v4
	v_mov_b32_e32 v16, v4
	v_mov_b32_e32 v17, v4
	v_mov_b32_e32 v18, v4
	v_mov_b32_e32 v19, v4
	v_mov_b32_e32 v8, v4
	v_mov_b32_e32 v9, v4
	v_mov_b32_e32 v10, v4
	v_mov_b32_e32 v11, v4
	v_mov_b32_e32 v20, v4
	v_mov_b32_e32 v21, v4
	v_mov_b32_e32 v22, v4
	v_mov_b32_e32 v23, v4
	v_mov_b32_e32 v12, v4
	v_mov_b32_e32 v13, v4
	v_mov_b32_e32 v14, v4
	v_mov_b32_e32 v15, v4
	v_mov_b32_e32 v24, v4
	v_mov_b32_e32 v25, v4
	v_mov_b32_e32 v26, v4
	v_mov_b32_e32 v27, v4
	v_mov_b32_e32 v28, v4
	v_mov_b32_e32 v29, v4
	v_mov_b32_e32 v30, v4
	v_mov_b32_e32 v31, v4
	v_mov_b32_e32 v32, v4
	v_mov_b32_e32 v33, v4
	v_mov_b32_e32 v34, v4
	v_mov_b32_e32 v35, v4
	v_mov_b32_e32 v68, v4
	v_mov_b32_e32 v69, v4
	v_mov_b32_e32 v70, v4
	v_mov_b32_e32 v71, v4
	v_mov_b32_e32 v72, v4
	v_mov_b32_e32 v73, v4
	v_mov_b32_e32 v74, v4
	v_mov_b32_e32 v75, v4
	v_mov_b32_e32 v76, v4
	v_mov_b32_e32 v77, v4
	v_mov_b32_e32 v78, v4
	v_mov_b32_e32 v79, v4
	v_mov_b32_e32 v80, v4
	v_mov_b32_e32 v81, v4
	v_mov_b32_e32 v82, v4
	v_mov_b32_e32 v83, v4
	v_mov_b32_e32 v84, v4
	v_mov_b32_e32 v85, v4
	v_mov_b32_e32 v86, v4
	v_mov_b32_e32 v87, v4
	v_mov_b32_e32 v88, v4
	v_mov_b32_e32 v89, v4
	v_mov_b32_e32 v90, v4
	v_mov_b32_e32 v91, v4
	v_mov_b32_e32 v92, v4
	v_mov_b32_e32 v93, v4
	v_mov_b32_e32 v94, v4
	v_mov_b32_e32 v95, v4
	v_mov_b32_e32 v96, v4
	v_mov_b32_e32 v97, v4
	v_mov_b32_e32 v98, v4
	v_mov_b32_e32 v99, v4
	v_mov_b32_e32 v36, v4
	v_mov_b32_e32 v37, v4
	v_mov_b32_e32 v38, v4
	v_mov_b32_e32 v39, v4
	v_mov_b32_e32 v44, v4
	v_mov_b32_e32 v45, v4
	v_mov_b32_e32 v46, v4
	v_mov_b32_e32 v47, v4
	v_mov_b32_e32 v40, v4
	v_mov_b32_e32 v41, v4
	v_mov_b32_e32 v42, v4
	v_mov_b32_e32 v43, v4
	v_mov_b32_e32 v48, v4
	v_mov_b32_e32 v49, v4
	v_mov_b32_e32 v50, v4
	v_mov_b32_e32 v51, v4
	v_mov_b32_e32 v52, v4
	v_mov_b32_e32 v53, v4
	v_mov_b32_e32 v54, v4
	v_mov_b32_e32 v55, v4
	v_mov_b32_e32 v60, v4
	v_mov_b32_e32 v61, v4
	v_mov_b32_e32 v62, v4
	v_mov_b32_e32 v63, v4
	v_mov_b32_e32 v56, v4
	v_mov_b32_e32 v57, v4
	v_mov_b32_e32 v58, v4
	v_mov_b32_e32 v59, v4
	v_mov_b32_e32 v64, v4
	v_mov_b32_e32 v65, v4
	v_mov_b32_e32 v66, v4
	v_mov_b32_e32 v67, v4
	v_mov_b32_e32 v100, v4
	v_mov_b32_e32 v101, v4
	v_mov_b32_e32 v102, v4
	v_mov_b32_e32 v103, v4
	v_mov_b32_e32 v104, v4
	v_mov_b32_e32 v105, v4
	v_mov_b32_e32 v106, v4
	v_mov_b32_e32 v107, v4
	v_mov_b32_e32 v108, v4
	v_mov_b32_e32 v109, v4
	v_mov_b32_e32 v110, v4
	v_mov_b32_e32 v111, v4
	v_mov_b32_e32 v112, v4
	v_mov_b32_e32 v113, v4
	v_mov_b32_e32 v114, v4
	v_mov_b32_e32 v115, v4
	v_mov_b32_e32 v116, v4
	v_mov_b32_e32 v117, v4
	v_mov_b32_e32 v118, v4
	v_mov_b32_e32 v119, v4
	v_mov_b32_e32 v120, v4
	v_mov_b32_e32 v121, v4
	v_mov_b32_e32 v122, v4
	v_mov_b32_e32 v123, v4
	v_mov_b32_e32 v124, v4
	v_mov_b32_e32 v125, v4
	v_mov_b32_e32 v126, v4
	v_mov_b32_e32 v127, v4
	v_mov_b32_e32 v128, v4
	v_mov_b32_e32 v129, v4
	v_mov_b32_e32 v130, v4
	v_mov_b32_e32 v131, v4
	.p2align	6
